# RWKV scan inner loop rewritten by hand: y partials fill DPP hazard slots, LDS reads issued in bursts per 2 steps, compiler nops removed; same f32 math/order per step except y reduction delay
# speedup vs baseline: 1.0340x; 1.0340x over previous
; __device__ __forceinline__ void phase_scan(const Params& P, char* smem) {
;     ...
;     SCAN_LOADB(0, 0)
;     float yprev = 0.f;
; #pragma unroll
;     for (int j = 0; j < 16; ++j) {
;       if (j + 1 < 16) {
;         SCAN_LOADB(j + 1, (j + 1) & 1)
;       }
;       __builtin_amdgcn_sched_barrier(0);
; #pragma unroll
;       for (int u = 0; u < 2; ++u) {
;         const int sl2 = j & 1;
;         const int st = j * 2 + u;
;         const f32x4 a4 = La[sl2][u], b4 = Lb[sl2][u], w4 = Lw[sl2][u], kd = Lk[sl2][u], r4 = Lr[sl2][u];
;         const float vv = Lv[sl2][u];
;         f32x2 p = S01 * a4.xy;
;         p = S23 * a4.zw + p;
;         float sa = p.x + p.y;
;         sa += dppf(sa, 0); yprev += dppf(yprev, 0);
;         sa += dppf(sa, 1); yprev += dppf(yprev, 1);
;         sa += dppf(sa, 2); yprev += dppf(yprev, 2);
;         sa += dppf(sa, 3); yprev += dppf(yprev, 3);
;         if (st >= 1 && st <= 16) ykeep0 = (kq == st - 1) ? yprev : ykeep0;
;         if (st >= 17) ykeep1 = (kq == st - 17) ? yprev : ykeep1;
;         const f32x2 sa2 = (f32x2){sa, sa}, vv2 = (f32x2){vv, vv};
;         const f32x2 t01 = sa2 * b4.xy + vv2 * kd.xy;
;         const f32x2 t23 = sa2 * b4.zw + vv2 * kd.zw;
;         S01 = S01 * w4.xy + t01;
;         S23 = S23 * w4.zw + t23;
;         f32x2 q = S01 * r4.xy;
;         q = S23 * r4.zw + q;
;         yprev = q.x + q.y;
;       }
.LBB0_1306:
	ds_read_b128 v[46:49], v34 offset:1024
	ds_read_b128 v[66:69], v34 offset:2560
	ds_read2st64_b32 v[86:87], v35 offset0:3 offset1:9
	ds_read_b128 v[54:57], v34 offset:512
	ds_read_b128 v[50:53], v34 offset:256
	ds_read_b128 v[58:61], v34 offset:1280
	ds_read_b128 v[62:65], v34
	ds_read_b128 v[74:77], v34 offset:2048
	ds_read_b128 v[70:73], v34 offset:1792
	ds_read_b128 v[78:81], v34 offset:2816
	ds_read_b128 v[82:85], v34 offset:1536
	s_waitcnt lgkmcnt(0)
	v_pk_mul_f32 v[130:131], v[30:31], v[46:47]
	v_pk_mul_f32 v[54:55], v[54:55], v[86:87] op_sel_hi:[1,0]
	v_pk_fma_f32 v[130:131], v[32:33], v[48:49], v[130:131]
	v_pk_mul_f32 v[56:57], v[56:57], v[86:87] op_sel_hi:[1,0]
	v_add_f32_e32 v130, v130, v131
	v_pk_fma_f32 v[54:55], v[30:31], v[50:51], v[54:55]
	v_pk_fma_f32 v[56:57], v[32:33], v[52:53], v[56:57]
	v_add_f32_dpp v130, v130, v130 quad_perm:[1,0,3,2] row_mask:0xf bank_mask:0xf bound_ctrl:1
	s_nop 0
	s_nop 0
	v_add_f32_dpp v130, v130, v130 quad_perm:[2,3,0,1] row_mask:0xf bank_mask:0xf bound_ctrl:1
	s_nop 0
	s_nop 0
	v_add_f32_dpp v130, v130, v130 row_half_mirror row_mask:0xf bank_mask:0xf bound_ctrl:1
	s_nop 0
	s_nop 0
	v_add_f32_dpp v130, v130, v130 row_mirror row_mask:0xf bank_mask:0xf bound_ctrl:1
	v_pk_fma_f32 v[30:31], v[58:59], v[130:131], v[54:55] op_sel_hi:[1,0,1]
	v_pk_fma_f32 v[32:33], v[60:61], v[130:131], v[56:57] op_sel_hi:[1,0,1]
	ds_read_b128 v[88:91], v34 offset:4096
	ds_read_b128 v[108:111], v34 offset:5632
	ds_read2st64_b32 v[128:129], v35 offset0:15 offset1:21
	ds_read_b128 v[96:99], v34 offset:3584
	ds_read_b128 v[92:95], v34 offset:3328
	ds_read_b128 v[100:103], v34 offset:4352
	ds_read_b128 v[104:107], v34 offset:3072
	ds_read_b128 v[116:119], v34 offset:5120
	ds_read_b128 v[112:115], v34 offset:4864
	ds_read_b128 v[120:123], v34 offset:5888
	ds_read_b128 v[124:127], v34 offset:4608
	v_pk_mul_f32 v[130:131], v[30:31], v[66:67]
	v_pk_mul_f32 v[74:75], v[74:75], v[86:87] op_sel:[0,1] op_sel_hi:[1,1]
	v_pk_fma_f32 v[130:131], v[32:33], v[68:69], v[130:131]
	v_pk_mul_f32 v[76:77], v[76:77], v[86:87] op_sel:[0,1] op_sel_hi:[1,1]
	v_add_f32_e32 v130, v130, v131
	v_pk_fma_f32 v[74:75], v[30:31], v[70:71], v[74:75]
	v_pk_fma_f32 v[76:77], v[32:33], v[72:73], v[76:77]
	v_add_f32_dpp v130, v130, v130 quad_perm:[1,0,3,2] row_mask:0xf bank_mask:0xf bound_ctrl:1
	s_nop 0
	v_pk_mul_f32 v[134:135], v[62:63], v[30:31]
	v_add_f32_dpp v130, v130, v130 quad_perm:[2,3,0,1] row_mask:0xf bank_mask:0xf bound_ctrl:1
	s_nop 0
	v_pk_fma_f32 v[134:135], v[64:65], v[32:33], v[134:135]
	v_add_f32_dpp v130, v130, v130 row_half_mirror row_mask:0xf bank_mask:0xf bound_ctrl:1
	s_nop 0
	v_add_f32_e32 v134, v134, v135
	v_add_f32_dpp v130, v130, v130 row_mirror row_mask:0xf bank_mask:0xf bound_ctrl:1
	v_pk_fma_f32 v[30:31], v[78:79], v[130:131], v[74:75] op_sel_hi:[1,0,1]
	v_pk_fma_f32 v[32:33], v[80:81], v[130:131], v[76:77] op_sel_hi:[1,0,1]
	s_waitcnt lgkmcnt(0)
	v_pk_mul_f32 v[130:131], v[30:31], v[88:89]
	v_pk_mul_f32 v[96:97], v[96:97], v[128:129] op_sel_hi:[1,0]
	v_pk_fma_f32 v[130:131], v[32:33], v[90:91], v[130:131]
	v_pk_mul_f32 v[98:99], v[98:99], v[128:129] op_sel_hi:[1,0]
	v_add_f32_e32 v130, v130, v131
	v_pk_fma_f32 v[96:97], v[30:31], v[92:93], v[96:97]
	v_pk_fma_f32 v[98:99], v[32:33], v[94:95], v[98:99]
	v_add_f32_dpp v130, v130, v130 quad_perm:[1,0,3,2] row_mask:0xf bank_mask:0xf bound_ctrl:1
	v_add_f32_dpp v134, v134, v134 quad_perm:[1,0,3,2] row_mask:0xf bank_mask:0xf bound_ctrl:1
	v_pk_mul_f32 v[132:133], v[82:83], v[30:31]
	v_add_f32_dpp v130, v130, v130 quad_perm:[2,3,0,1] row_mask:0xf bank_mask:0xf bound_ctrl:1
	v_add_f32_dpp v134, v134, v134 quad_perm:[2,3,0,1] row_mask:0xf bank_mask:0xf bound_ctrl:1
	v_pk_fma_f32 v[132:133], v[84:85], v[32:33], v[132:133]
	v_add_f32_dpp v130, v130, v130 row_half_mirror row_mask:0xf bank_mask:0xf bound_ctrl:1
	v_add_f32_dpp v134, v134, v134 row_half_mirror row_mask:0xf bank_mask:0xf bound_ctrl:1
	v_add_f32_e32 v132, v132, v133
	v_add_f32_dpp v130, v130, v130 row_mirror row_mask:0xf bank_mask:0xf bound_ctrl:1
	v_add_f32_dpp v134, v134, v134 row_mirror row_mask:0xf bank_mask:0xf bound_ctrl:1
	v_cndmask_b32_e64 v44, 0, v134, s[36:37]
	v_pk_fma_f32 v[30:31], v[100:101], v[130:131], v[96:97] op_sel_hi:[1,0,1]
	v_pk_fma_f32 v[32:33], v[102:103], v[130:131], v[98:99] op_sel_hi:[1,0,1]
	ds_read_b128 v[46:49], v34 offset:7168
	ds_read_b128 v[66:69], v34 offset:8704
	ds_read2st64_b32 v[86:87], v35 offset0:27 offset1:33
	ds_read_b128 v[54:57], v34 offset:6656
	ds_read_b128 v[50:53], v34 offset:6400
	ds_read_b128 v[58:61], v34 offset:7424
	ds_read_b128 v[62:65], v34 offset:6144
	ds_read_b128 v[74:77], v34 offset:8192
	ds_read_b128 v[70:73], v34 offset:7936
	ds_read_b128 v[78:81], v34 offset:8960
	ds_read_b128 v[82:85], v34 offset:7680
	v_pk_mul_f32 v[130:131], v[30:31], v[108:109]
	v_pk_mul_f32 v[116:117], v[116:117], v[128:129] op_sel:[0,1] op_sel_hi:[1,1]
	v_pk_fma_f32 v[130:131], v[32:33], v[110:111], v[130:131]
	v_pk_mul_f32 v[118:119], v[118:119], v[128:129] op_sel:[0,1] op_sel_hi:[1,1]
	v_add_f32_e32 v130, v130, v131
	v_pk_fma_f32 v[116:117], v[30:31], v[112:113], v[116:117]
	v_pk_fma_f32 v[118:119], v[32:33], v[114:115], v[118:119]
	v_add_f32_dpp v130, v130, v130 quad_perm:[1,0,3,2] row_mask:0xf bank_mask:0xf bound_ctrl:1
	v_add_f32_dpp v132, v132, v132 quad_perm:[1,0,3,2] row_mask:0xf bank_mask:0xf bound_ctrl:1
	v_pk_mul_f32 v[134:135], v[104:105], v[30:31]
	v_add_f32_dpp v130, v130, v130 quad_perm:[2,3,0,1] row_mask:0xf bank_mask:0xf bound_ctrl:1
	v_add_f32_dpp v132, v132, v132 quad_perm:[2,3,0,1] row_mask:0xf bank_mask:0xf bound_ctrl:1
	v_pk_fma_f32 v[134:135], v[106:107], v[32:33], v[134:135]
	v_add_f32_dpp v130, v130, v130 row_half_mirror row_mask:0xf bank_mask:0xf bound_ctrl:1
	v_add_f32_dpp v132, v132, v132 row_half_mirror row_mask:0xf bank_mask:0xf bound_ctrl:1
	v_add_f32_e32 v134, v134, v135
	v_add_f32_dpp v130, v130, v130 row_mirror row_mask:0xf bank_mask:0xf bound_ctrl:1
	v_add_f32_dpp v132, v132, v132 row_mirror row_mask:0xf bank_mask:0xf bound_ctrl:1
	v_cndmask_b32_e64 v44, v44, v132, s[4:5]
	v_pk_fma_f32 v[30:31], v[120:121], v[130:131], v[116:117] op_sel_hi:[1,0,1]
	v_pk_fma_f32 v[32:33], v[122:123], v[130:131], v[118:119] op_sel_hi:[1,0,1]
	s_waitcnt lgkmcnt(0)
; __device__ __forceinline__ void phase_scan(const Params& P, char* smem) {
;     ...
;     for (int j = 0; j < 16; ++j) {
;       if (j + 1 < 16) {
;         SCAN_LOADB(j + 1, (j + 1) & 1)
;       }
;       __builtin_amdgcn_sched_barrier(0);
; #pragma unroll
;       for (int u = 0; u < 2; ++u) {
;         const int sl2 = j & 1;
;         const int st = j * 2 + u;
;         const f32x4 a4 = La[sl2][u], b4 = Lb[sl2][u], w4 = Lw[sl2][u], kd = Lk[sl2][u], r4 = Lr[sl2][u];
;         const float vv = Lv[sl2][u];
;         f32x2 p = S01 * a4.xy;
;         p = S23 * a4.zw + p;
;         float sa = p.x + p.y;
;         sa += dppf(sa, 0); yprev += dppf(yprev, 0);
;         sa += dppf(sa, 1); yprev += dppf(yprev, 1);
;         sa += dppf(sa, 2); yprev += dppf(yprev, 2);
;         sa += dppf(sa, 3); yprev += dppf(yprev, 3);
;         if (st >= 1 && st <= 16) ykeep0 = (kq == st - 1) ? yprev : ykeep0;
;         if (st >= 17) ykeep1 = (kq == st - 17) ? yprev : ykeep1;
;         const f32x2 sa2 = (f32x2){sa, sa}, vv2 = (f32x2){vv, vv};
;         const f32x2 t01 = sa2 * b4.xy + vv2 * kd.xy;
;         const f32x2 t23 = sa2 * b4.zw + vv2 * kd.zw;
;         S01 = S01 * w4.xy + t01;
;         S23 = S23 * w4.zw + t23;
;         f32x2 q = S01 * r4.xy;
;         q = S23 * r4.zw + q;
;         yprev = q.x + q.y;
;       }
	v_pk_mul_f32 v[130:131], v[30:31], v[46:47]
	v_pk_mul_f32 v[54:55], v[54:55], v[86:87] op_sel_hi:[1,0]
	v_pk_fma_f32 v[130:131], v[32:33], v[48:49], v[130:131]
	v_pk_mul_f32 v[56:57], v[56:57], v[86:87] op_sel_hi:[1,0]
	v_add_f32_e32 v130, v130, v131
	v_pk_fma_f32 v[54:55], v[30:31], v[50:51], v[54:55]
	v_pk_fma_f32 v[56:57], v[32:33], v[52:53], v[56:57]
	v_add_f32_dpp v130, v130, v130 quad_perm:[1,0,3,2] row_mask:0xf bank_mask:0xf bound_ctrl:1
	v_add_f32_dpp v134, v134, v134 quad_perm:[1,0,3,2] row_mask:0xf bank_mask:0xf bound_ctrl:1
	v_pk_mul_f32 v[132:133], v[124:125], v[30:31]
	v_add_f32_dpp v130, v130, v130 quad_perm:[2,3,0,1] row_mask:0xf bank_mask:0xf bound_ctrl:1
	v_add_f32_dpp v134, v134, v134 quad_perm:[2,3,0,1] row_mask:0xf bank_mask:0xf bound_ctrl:1
	v_pk_fma_f32 v[132:133], v[126:127], v[32:33], v[132:133]
	v_add_f32_dpp v130, v130, v130 row_half_mirror row_mask:0xf bank_mask:0xf bound_ctrl:1
	v_add_f32_dpp v134, v134, v134 row_half_mirror row_mask:0xf bank_mask:0xf bound_ctrl:1
	v_add_f32_e32 v132, v132, v133
	v_add_f32_dpp v130, v130, v130 row_mirror row_mask:0xf bank_mask:0xf bound_ctrl:1
	v_add_f32_dpp v134, v134, v134 row_mirror row_mask:0xf bank_mask:0xf bound_ctrl:1
	v_cndmask_b32_e64 v44, v44, v134, s[6:7]
	v_pk_fma_f32 v[30:31], v[58:59], v[130:131], v[54:55] op_sel_hi:[1,0,1]
	v_pk_fma_f32 v[32:33], v[60:61], v[130:131], v[56:57] op_sel_hi:[1,0,1]
	ds_read_b128 v[88:91], v34 offset:10240
	ds_read_b128 v[108:111], v34 offset:11776
	ds_read2st64_b32 v[128:129], v35 offset0:39 offset1:45
	ds_read_b128 v[96:99], v34 offset:9728
	ds_read_b128 v[92:95], v34 offset:9472
	ds_read_b128 v[100:103], v34 offset:10496
	ds_read_b128 v[104:107], v34 offset:9216
	ds_read_b128 v[116:119], v34 offset:11264
	ds_read_b128 v[112:115], v34 offset:11008
	ds_read_b128 v[120:123], v34 offset:12032
	ds_read_b128 v[124:127], v34 offset:10752
	v_pk_mul_f32 v[130:131], v[30:31], v[66:67]
	v_pk_mul_f32 v[74:75], v[74:75], v[86:87] op_sel:[0,1] op_sel_hi:[1,1]
	v_pk_fma_f32 v[130:131], v[32:33], v[68:69], v[130:131]
	v_pk_mul_f32 v[76:77], v[76:77], v[86:87] op_sel:[0,1] op_sel_hi:[1,1]
	v_add_f32_e32 v130, v130, v131
	v_pk_fma_f32 v[74:75], v[30:31], v[70:71], v[74:75]
	v_pk_fma_f32 v[76:77], v[32:33], v[72:73], v[76:77]
	v_add_f32_dpp v130, v130, v130 quad_perm:[1,0,3,2] row_mask:0xf bank_mask:0xf bound_ctrl:1
	v_add_f32_dpp v132, v132, v132 quad_perm:[1,0,3,2] row_mask:0xf bank_mask:0xf bound_ctrl:1
	v_pk_mul_f32 v[134:135], v[62:63], v[30:31]
	v_add_f32_dpp v130, v130, v130 quad_perm:[2,3,0,1] row_mask:0xf bank_mask:0xf bound_ctrl:1
	v_add_f32_dpp v132, v132, v132 quad_perm:[2,3,0,1] row_mask:0xf bank_mask:0xf bound_ctrl:1
	v_pk_fma_f32 v[134:135], v[64:65], v[32:33], v[134:135]
	v_add_f32_dpp v130, v130, v130 row_half_mirror row_mask:0xf bank_mask:0xf bound_ctrl:1
	v_add_f32_dpp v132, v132, v132 row_half_mirror row_mask:0xf bank_mask:0xf bound_ctrl:1
	v_add_f32_e32 v134, v134, v135
	v_add_f32_dpp v130, v130, v130 row_mirror row_mask:0xf bank_mask:0xf bound_ctrl:1
	v_add_f32_dpp v132, v132, v132 row_mirror row_mask:0xf bank_mask:0xf bound_ctrl:1
	v_cndmask_b32_e64 v44, v44, v132, s[8:9]
	v_pk_fma_f32 v[30:31], v[78:79], v[130:131], v[74:75] op_sel_hi:[1,0,1]
	v_pk_fma_f32 v[32:33], v[80:81], v[130:131], v[76:77] op_sel_hi:[1,0,1]
	s_waitcnt lgkmcnt(0)
	v_pk_mul_f32 v[130:131], v[30:31], v[88:89]
	v_pk_mul_f32 v[96:97], v[96:97], v[128:129] op_sel_hi:[1,0]
	v_pk_fma_f32 v[130:131], v[32:33], v[90:91], v[130:131]
	v_pk_mul_f32 v[98:99], v[98:99], v[128:129] op_sel_hi:[1,0]
	v_add_f32_e32 v130, v130, v131
	v_pk_fma_f32 v[96:97], v[30:31], v[92:93], v[96:97]
	v_pk_fma_f32 v[98:99], v[32:33], v[94:95], v[98:99]
	v_add_f32_dpp v130, v130, v130 quad_perm:[1,0,3,2] row_mask:0xf bank_mask:0xf bound_ctrl:1
	v_add_f32_dpp v134, v134, v134 quad_perm:[1,0,3,2] row_mask:0xf bank_mask:0xf bound_ctrl:1
	v_pk_mul_f32 v[132:133], v[82:83], v[30:31]
	v_add_f32_dpp v130, v130, v130 quad_perm:[2,3,0,1] row_mask:0xf bank_mask:0xf bound_ctrl:1
	v_add_f32_dpp v134, v134, v134 quad_perm:[2,3,0,1] row_mask:0xf bank_mask:0xf bound_ctrl:1
	v_pk_fma_f32 v[132:133], v[84:85], v[32:33], v[132:133]
	v_add_f32_dpp v130, v130, v130 row_half_mirror row_mask:0xf bank_mask:0xf bound_ctrl:1
	v_add_f32_dpp v134, v134, v134 row_half_mirror row_mask:0xf bank_mask:0xf bound_ctrl:1
	v_add_f32_e32 v132, v132, v133
	v_add_f32_dpp v130, v130, v130 row_mirror row_mask:0xf bank_mask:0xf bound_ctrl:1
	v_add_f32_dpp v134, v134, v134 row_mirror row_mask:0xf bank_mask:0xf bound_ctrl:1
	v_cndmask_b32_e64 v44, v44, v134, s[12:13]
	v_pk_fma_f32 v[30:31], v[100:101], v[130:131], v[96:97] op_sel_hi:[1,0,1]
	v_pk_fma_f32 v[32:33], v[102:103], v[130:131], v[98:99] op_sel_hi:[1,0,1]
	ds_read_b128 v[46:49], v34 offset:13312
	ds_read_b128 v[66:69], v34 offset:14848
	ds_read2st64_b32 v[86:87], v35 offset0:51 offset1:57
	ds_read_b128 v[54:57], v34 offset:12800
	ds_read_b128 v[50:53], v34 offset:12544
	ds_read_b128 v[58:61], v34 offset:13568
	ds_read_b128 v[62:65], v34 offset:12288
	ds_read_b128 v[74:77], v34 offset:14336
	ds_read_b128 v[70:73], v34 offset:14080
	ds_read_b128 v[78:81], v34 offset:15104
	ds_read_b128 v[82:85], v34 offset:13824
	v_pk_mul_f32 v[130:131], v[30:31], v[108:109]
	v_pk_mul_f32 v[116:117], v[116:117], v[128:129] op_sel:[0,1] op_sel_hi:[1,1]
	v_pk_fma_f32 v[130:131], v[32:33], v[110:111], v[130:131]
	v_pk_mul_f32 v[118:119], v[118:119], v[128:129] op_sel:[0,1] op_sel_hi:[1,1]
	v_add_f32_e32 v130, v130, v131
	v_pk_fma_f32 v[116:117], v[30:31], v[112:113], v[116:117]
	v_pk_fma_f32 v[118:119], v[32:33], v[114:115], v[118:119]
	v_add_f32_dpp v130, v130, v130 quad_perm:[1,0,3,2] row_mask:0xf bank_mask:0xf bound_ctrl:1
	v_add_f32_dpp v132, v132, v132 quad_perm:[1,0,3,2] row_mask:0xf bank_mask:0xf bound_ctrl:1
	v_pk_mul_f32 v[134:135], v[104:105], v[30:31]
	v_add_f32_dpp v130, v130, v130 quad_perm:[2,3,0,1] row_mask:0xf bank_mask:0xf bound_ctrl:1
	v_add_f32_dpp v132, v132, v132 quad_perm:[2,3,0,1] row_mask:0xf bank_mask:0xf bound_ctrl:1
	v_pk_fma_f32 v[134:135], v[106:107], v[32:33], v[134:135]
	v_add_f32_dpp v130, v130, v130 row_half_mirror row_mask:0xf bank_mask:0xf bound_ctrl:1
	v_add_f32_dpp v132, v132, v132 row_half_mirror row_mask:0xf bank_mask:0xf bound_ctrl:1
	v_add_f32_e32 v134, v134, v135
	v_add_f32_dpp v130, v130, v130 row_mirror row_mask:0xf bank_mask:0xf bound_ctrl:1
	v_add_f32_dpp v132, v132, v132 row_mirror row_mask:0xf bank_mask:0xf bound_ctrl:1
	v_cndmask_b32_e64 v44, v44, v132, s[14:15]
	v_pk_fma_f32 v[30:31], v[120:121], v[130:131], v[116:117] op_sel_hi:[1,0,1]
	v_pk_fma_f32 v[32:33], v[122:123], v[130:131], v[118:119] op_sel_hi:[1,0,1]
	s_waitcnt lgkmcnt(0)
; __device__ __forceinline__ void phase_scan(const Params& P, char* smem) {
;     ...
;     for (int j = 0; j < 16; ++j) {
;       if (j + 1 < 16) {
;         SCAN_LOADB(j + 1, (j + 1) & 1)
;       }
;       __builtin_amdgcn_sched_barrier(0);
; #pragma unroll
;       for (int u = 0; u < 2; ++u) {
;         const int sl2 = j & 1;
;         const int st = j * 2 + u;
;         const f32x4 a4 = La[sl2][u], b4 = Lb[sl2][u], w4 = Lw[sl2][u], kd = Lk[sl2][u], r4 = Lr[sl2][u];
;         const float vv = Lv[sl2][u];
;         f32x2 p = S01 * a4.xy;
;         p = S23 * a4.zw + p;
;         float sa = p.x + p.y;
;         sa += dppf(sa, 0); yprev += dppf(yprev, 0);
;         sa += dppf(sa, 1); yprev += dppf(yprev, 1);
;         sa += dppf(sa, 2); yprev += dppf(yprev, 2);
;         sa += dppf(sa, 3); yprev += dppf(yprev, 3);
;         if (st >= 1 && st <= 16) ykeep0 = (kq == st - 1) ? yprev : ykeep0;
;         if (st >= 17) ykeep1 = (kq == st - 17) ? yprev : ykeep1;
;         const f32x2 sa2 = (f32x2){sa, sa}, vv2 = (f32x2){vv, vv};
;         const f32x2 t01 = sa2 * b4.xy + vv2 * kd.xy;
;         const f32x2 t23 = sa2 * b4.zw + vv2 * kd.zw;
;         S01 = S01 * w4.xy + t01;
;         S23 = S23 * w4.zw + t23;
;         f32x2 q = S01 * r4.xy;
;         q = S23 * r4.zw + q;
;         yprev = q.x + q.y;
;       }
	v_pk_mul_f32 v[130:131], v[30:31], v[46:47]
	v_pk_mul_f32 v[54:55], v[54:55], v[86:87] op_sel_hi:[1,0]
	v_pk_fma_f32 v[130:131], v[32:33], v[48:49], v[130:131]
	v_pk_mul_f32 v[56:57], v[56:57], v[86:87] op_sel_hi:[1,0]
	v_add_f32_e32 v130, v130, v131
	v_pk_fma_f32 v[54:55], v[30:31], v[50:51], v[54:55]
	v_pk_fma_f32 v[56:57], v[32:33], v[52:53], v[56:57]
	v_add_f32_dpp v130, v130, v130 quad_perm:[1,0,3,2] row_mask:0xf bank_mask:0xf bound_ctrl:1
	v_add_f32_dpp v134, v134, v134 quad_perm:[1,0,3,2] row_mask:0xf bank_mask:0xf bound_ctrl:1
	v_pk_mul_f32 v[132:133], v[124:125], v[30:31]
	v_add_f32_dpp v130, v130, v130 quad_perm:[2,3,0,1] row_mask:0xf bank_mask:0xf bound_ctrl:1
	v_add_f32_dpp v134, v134, v134 quad_perm:[2,3,0,1] row_mask:0xf bank_mask:0xf bound_ctrl:1
	v_pk_fma_f32 v[132:133], v[126:127], v[32:33], v[132:133]
	v_add_f32_dpp v130, v130, v130 row_half_mirror row_mask:0xf bank_mask:0xf bound_ctrl:1
	v_add_f32_dpp v134, v134, v134 row_half_mirror row_mask:0xf bank_mask:0xf bound_ctrl:1
	v_add_f32_e32 v132, v132, v133
	v_add_f32_dpp v130, v130, v130 row_mirror row_mask:0xf bank_mask:0xf bound_ctrl:1
	v_add_f32_dpp v134, v134, v134 row_mirror row_mask:0xf bank_mask:0xf bound_ctrl:1
	v_cndmask_b32_e64 v44, v44, v134, s[16:17]
	v_pk_fma_f32 v[30:31], v[58:59], v[130:131], v[54:55] op_sel_hi:[1,0,1]
	v_pk_fma_f32 v[32:33], v[60:61], v[130:131], v[56:57] op_sel_hi:[1,0,1]
	ds_read_b128 v[88:91], v34 offset:16384
	ds_read_b128 v[108:111], v34 offset:17920
	ds_read2st64_b32 v[128:129], v35 offset0:63 offset1:69
	ds_read_b128 v[96:99], v34 offset:15872
	ds_read_b128 v[92:95], v34 offset:15616
	ds_read_b128 v[100:103], v34 offset:16640
	ds_read_b128 v[104:107], v34 offset:15360
	ds_read_b128 v[116:119], v34 offset:17408
	ds_read_b128 v[112:115], v34 offset:17152
	ds_read_b128 v[120:123], v34 offset:18176
	ds_read_b128 v[124:127], v34 offset:16896
	v_pk_mul_f32 v[130:131], v[30:31], v[66:67]
	v_pk_mul_f32 v[74:75], v[74:75], v[86:87] op_sel:[0,1] op_sel_hi:[1,1]
	v_pk_fma_f32 v[130:131], v[32:33], v[68:69], v[130:131]
	v_pk_mul_f32 v[76:77], v[76:77], v[86:87] op_sel:[0,1] op_sel_hi:[1,1]
	v_add_f32_e32 v130, v130, v131
	v_pk_fma_f32 v[74:75], v[30:31], v[70:71], v[74:75]
	v_pk_fma_f32 v[76:77], v[32:33], v[72:73], v[76:77]
	v_add_f32_dpp v130, v130, v130 quad_perm:[1,0,3,2] row_mask:0xf bank_mask:0xf bound_ctrl:1
	v_add_f32_dpp v132, v132, v132 quad_perm:[1,0,3,2] row_mask:0xf bank_mask:0xf bound_ctrl:1
	v_pk_mul_f32 v[134:135], v[62:63], v[30:31]
	v_add_f32_dpp v130, v130, v130 quad_perm:[2,3,0,1] row_mask:0xf bank_mask:0xf bound_ctrl:1
	v_add_f32_dpp v132, v132, v132 quad_perm:[2,3,0,1] row_mask:0xf bank_mask:0xf bound_ctrl:1
	v_pk_fma_f32 v[134:135], v[64:65], v[32:33], v[134:135]
	v_add_f32_dpp v130, v130, v130 row_half_mirror row_mask:0xf bank_mask:0xf bound_ctrl:1
	v_add_f32_dpp v132, v132, v132 row_half_mirror row_mask:0xf bank_mask:0xf bound_ctrl:1
	v_add_f32_e32 v134, v134, v135
	v_add_f32_dpp v130, v130, v130 row_mirror row_mask:0xf bank_mask:0xf bound_ctrl:1
	v_add_f32_dpp v132, v132, v132 row_mirror row_mask:0xf bank_mask:0xf bound_ctrl:1
	v_cndmask_b32_e64 v44, v44, v132, s[18:19]
	v_pk_fma_f32 v[30:31], v[78:79], v[130:131], v[74:75] op_sel_hi:[1,0,1]
	v_pk_fma_f32 v[32:33], v[80:81], v[130:131], v[76:77] op_sel_hi:[1,0,1]
	s_waitcnt lgkmcnt(0)
	v_pk_mul_f32 v[130:131], v[30:31], v[88:89]
	v_pk_mul_f32 v[96:97], v[96:97], v[128:129] op_sel_hi:[1,0]
	v_pk_fma_f32 v[130:131], v[32:33], v[90:91], v[130:131]
	v_pk_mul_f32 v[98:99], v[98:99], v[128:129] op_sel_hi:[1,0]
	v_add_f32_e32 v130, v130, v131
	v_pk_fma_f32 v[96:97], v[30:31], v[92:93], v[96:97]
	v_pk_fma_f32 v[98:99], v[32:33], v[94:95], v[98:99]
	v_add_f32_dpp v130, v130, v130 quad_perm:[1,0,3,2] row_mask:0xf bank_mask:0xf bound_ctrl:1
	v_add_f32_dpp v134, v134, v134 quad_perm:[1,0,3,2] row_mask:0xf bank_mask:0xf bound_ctrl:1
	v_pk_mul_f32 v[132:133], v[82:83], v[30:31]
	v_add_f32_dpp v130, v130, v130 quad_perm:[2,3,0,1] row_mask:0xf bank_mask:0xf bound_ctrl:1
	v_add_f32_dpp v134, v134, v134 quad_perm:[2,3,0,1] row_mask:0xf bank_mask:0xf bound_ctrl:1
	v_pk_fma_f32 v[132:133], v[84:85], v[32:33], v[132:133]
	v_add_f32_dpp v130, v130, v130 row_half_mirror row_mask:0xf bank_mask:0xf bound_ctrl:1
	v_add_f32_dpp v134, v134, v134 row_half_mirror row_mask:0xf bank_mask:0xf bound_ctrl:1
	v_add_f32_e32 v132, v132, v133
	v_add_f32_dpp v130, v130, v130 row_mirror row_mask:0xf bank_mask:0xf bound_ctrl:1
	v_add_f32_dpp v134, v134, v134 row_mirror row_mask:0xf bank_mask:0xf bound_ctrl:1
	v_cndmask_b32_e64 v44, v44, v134, s[20:21]
	v_pk_fma_f32 v[30:31], v[100:101], v[130:131], v[96:97] op_sel_hi:[1,0,1]
	v_pk_fma_f32 v[32:33], v[102:103], v[130:131], v[98:99] op_sel_hi:[1,0,1]
	ds_read_b128 v[46:49], v34 offset:19456
	ds_read_b128 v[66:69], v34 offset:20992
	ds_read2st64_b32 v[86:87], v35 offset0:75 offset1:81
	ds_read_b128 v[54:57], v34 offset:18944
	ds_read_b128 v[50:53], v34 offset:18688
	ds_read_b128 v[58:61], v34 offset:19712
	ds_read_b128 v[62:65], v34 offset:18432
	ds_read_b128 v[74:77], v34 offset:20480
	ds_read_b128 v[70:73], v34 offset:20224
	ds_read_b128 v[78:81], v34 offset:21248
	ds_read_b128 v[82:85], v34 offset:19968
	v_pk_mul_f32 v[130:131], v[30:31], v[108:109]
	v_pk_mul_f32 v[116:117], v[116:117], v[128:129] op_sel:[0,1] op_sel_hi:[1,1]
	v_pk_fma_f32 v[130:131], v[32:33], v[110:111], v[130:131]
	v_pk_mul_f32 v[118:119], v[118:119], v[128:129] op_sel:[0,1] op_sel_hi:[1,1]
	v_add_f32_e32 v130, v130, v131
	v_pk_fma_f32 v[116:117], v[30:31], v[112:113], v[116:117]
	v_pk_fma_f32 v[118:119], v[32:33], v[114:115], v[118:119]
	v_add_f32_dpp v130, v130, v130 quad_perm:[1,0,3,2] row_mask:0xf bank_mask:0xf bound_ctrl:1
	v_add_f32_dpp v132, v132, v132 quad_perm:[1,0,3,2] row_mask:0xf bank_mask:0xf bound_ctrl:1
	v_pk_mul_f32 v[134:135], v[104:105], v[30:31]
	v_add_f32_dpp v130, v130, v130 quad_perm:[2,3,0,1] row_mask:0xf bank_mask:0xf bound_ctrl:1
	v_add_f32_dpp v132, v132, v132 quad_perm:[2,3,0,1] row_mask:0xf bank_mask:0xf bound_ctrl:1
	v_pk_fma_f32 v[134:135], v[106:107], v[32:33], v[134:135]
	v_add_f32_dpp v130, v130, v130 row_half_mirror row_mask:0xf bank_mask:0xf bound_ctrl:1
	v_add_f32_dpp v132, v132, v132 row_half_mirror row_mask:0xf bank_mask:0xf bound_ctrl:1
	v_add_f32_e32 v134, v134, v135
	v_add_f32_dpp v130, v130, v130 row_mirror row_mask:0xf bank_mask:0xf bound_ctrl:1
	v_add_f32_dpp v132, v132, v132 row_mirror row_mask:0xf bank_mask:0xf bound_ctrl:1
	v_cndmask_b32_e64 v44, v44, v132, s[22:23]
	v_pk_fma_f32 v[30:31], v[120:121], v[130:131], v[116:117] op_sel_hi:[1,0,1]
	v_pk_fma_f32 v[32:33], v[122:123], v[130:131], v[118:119] op_sel_hi:[1,0,1]
	s_waitcnt lgkmcnt(0)
; __device__ __forceinline__ void phase_scan(const Params& P, char* smem) {
;     ...
;     for (int j = 0; j < 16; ++j) {
;       if (j + 1 < 16) {
;         SCAN_LOADB(j + 1, (j + 1) & 1)
;       }
;       __builtin_amdgcn_sched_barrier(0);
; #pragma unroll
;       for (int u = 0; u < 2; ++u) {
;         const int sl2 = j & 1;
;         const int st = j * 2 + u;
;         const f32x4 a4 = La[sl2][u], b4 = Lb[sl2][u], w4 = Lw[sl2][u], kd = Lk[sl2][u], r4 = Lr[sl2][u];
;         const float vv = Lv[sl2][u];
;         f32x2 p = S01 * a4.xy;
;         p = S23 * a4.zw + p;
;         float sa = p.x + p.y;
;         sa += dppf(sa, 0); yprev += dppf(yprev, 0);
;         sa += dppf(sa, 1); yprev += dppf(yprev, 1);
;         sa += dppf(sa, 2); yprev += dppf(yprev, 2);
;         sa += dppf(sa, 3); yprev += dppf(yprev, 3);
;         if (st >= 1 && st <= 16) ykeep0 = (kq == st - 1) ? yprev : ykeep0;
;         if (st >= 17) ykeep1 = (kq == st - 17) ? yprev : ykeep1;
;         const f32x2 sa2 = (f32x2){sa, sa}, vv2 = (f32x2){vv, vv};
;         const f32x2 t01 = sa2 * b4.xy + vv2 * kd.xy;
;         const f32x2 t23 = sa2 * b4.zw + vv2 * kd.zw;
;         S01 = S01 * w4.xy + t01;
;         S23 = S23 * w4.zw + t23;
;         f32x2 q = S01 * r4.xy;
;         q = S23 * r4.zw + q;
;         yprev = q.x + q.y;
;       }
	v_pk_mul_f32 v[130:131], v[30:31], v[46:47]
	v_pk_mul_f32 v[54:55], v[54:55], v[86:87] op_sel_hi:[1,0]
	v_pk_fma_f32 v[130:131], v[32:33], v[48:49], v[130:131]
	v_pk_mul_f32 v[56:57], v[56:57], v[86:87] op_sel_hi:[1,0]
	v_add_f32_e32 v130, v130, v131
	v_pk_fma_f32 v[54:55], v[30:31], v[50:51], v[54:55]
	v_pk_fma_f32 v[56:57], v[32:33], v[52:53], v[56:57]
	v_add_f32_dpp v130, v130, v130 quad_perm:[1,0,3,2] row_mask:0xf bank_mask:0xf bound_ctrl:1
	v_add_f32_dpp v134, v134, v134 quad_perm:[1,0,3,2] row_mask:0xf bank_mask:0xf bound_ctrl:1
	v_pk_mul_f32 v[132:133], v[124:125], v[30:31]
	v_add_f32_dpp v130, v130, v130 quad_perm:[2,3,0,1] row_mask:0xf bank_mask:0xf bound_ctrl:1
	v_add_f32_dpp v134, v134, v134 quad_perm:[2,3,0,1] row_mask:0xf bank_mask:0xf bound_ctrl:1
	v_pk_fma_f32 v[132:133], v[126:127], v[32:33], v[132:133]
	v_add_f32_dpp v130, v130, v130 row_half_mirror row_mask:0xf bank_mask:0xf bound_ctrl:1
	v_add_f32_dpp v134, v134, v134 row_half_mirror row_mask:0xf bank_mask:0xf bound_ctrl:1
	v_add_f32_e32 v132, v132, v133
	v_add_f32_dpp v130, v130, v130 row_mirror row_mask:0xf bank_mask:0xf bound_ctrl:1
	v_add_f32_dpp v134, v134, v134 row_mirror row_mask:0xf bank_mask:0xf bound_ctrl:1
	v_cndmask_b32_e64 v44, v44, v134, s[24:25]
	v_pk_fma_f32 v[30:31], v[58:59], v[130:131], v[54:55] op_sel_hi:[1,0,1]
	v_pk_fma_f32 v[32:33], v[60:61], v[130:131], v[56:57] op_sel_hi:[1,0,1]
	ds_read_b128 v[88:91], v34 offset:22528
	ds_read_b128 v[108:111], v34 offset:24064
	ds_read2st64_b32 v[128:129], v35 offset0:87 offset1:93
	ds_read_b128 v[96:99], v34 offset:22016
	ds_read_b128 v[92:95], v34 offset:21760
	ds_read_b128 v[100:103], v34 offset:22784
	ds_read_b128 v[104:107], v34 offset:21504
	ds_read_b128 v[116:119], v34 offset:23552
	ds_read_b128 v[112:115], v34 offset:23296
	ds_read_b128 v[120:123], v34 offset:24320
	ds_read_b128 v[124:127], v34 offset:23040
	v_pk_mul_f32 v[130:131], v[30:31], v[66:67]
	v_pk_mul_f32 v[74:75], v[74:75], v[86:87] op_sel:[0,1] op_sel_hi:[1,1]
	v_pk_fma_f32 v[130:131], v[32:33], v[68:69], v[130:131]
	v_pk_mul_f32 v[76:77], v[76:77], v[86:87] op_sel:[0,1] op_sel_hi:[1,1]
	v_add_f32_e32 v130, v130, v131
	v_pk_fma_f32 v[74:75], v[30:31], v[70:71], v[74:75]
	v_pk_fma_f32 v[76:77], v[32:33], v[72:73], v[76:77]
	v_add_f32_dpp v130, v130, v130 quad_perm:[1,0,3,2] row_mask:0xf bank_mask:0xf bound_ctrl:1
	v_add_f32_dpp v132, v132, v132 quad_perm:[1,0,3,2] row_mask:0xf bank_mask:0xf bound_ctrl:1
	v_pk_mul_f32 v[134:135], v[62:63], v[30:31]
	v_add_f32_dpp v130, v130, v130 quad_perm:[2,3,0,1] row_mask:0xf bank_mask:0xf bound_ctrl:1
	v_add_f32_dpp v132, v132, v132 quad_perm:[2,3,0,1] row_mask:0xf bank_mask:0xf bound_ctrl:1
	v_pk_fma_f32 v[134:135], v[64:65], v[32:33], v[134:135]
	v_add_f32_dpp v130, v130, v130 row_half_mirror row_mask:0xf bank_mask:0xf bound_ctrl:1
	v_add_f32_dpp v132, v132, v132 row_half_mirror row_mask:0xf bank_mask:0xf bound_ctrl:1
	v_add_f32_e32 v134, v134, v135
	v_add_f32_dpp v130, v130, v130 row_mirror row_mask:0xf bank_mask:0xf bound_ctrl:1
	v_add_f32_dpp v132, v132, v132 row_mirror row_mask:0xf bank_mask:0xf bound_ctrl:1
	v_cndmask_b32_e64 v44, v44, v132, s[26:27]
	v_pk_fma_f32 v[30:31], v[78:79], v[130:131], v[74:75] op_sel_hi:[1,0,1]
	v_pk_fma_f32 v[32:33], v[80:81], v[130:131], v[76:77] op_sel_hi:[1,0,1]
	s_waitcnt lgkmcnt(0)
	v_pk_mul_f32 v[130:131], v[30:31], v[88:89]
	v_pk_mul_f32 v[96:97], v[96:97], v[128:129] op_sel_hi:[1,0]
	v_pk_fma_f32 v[130:131], v[32:33], v[90:91], v[130:131]
	v_pk_mul_f32 v[98:99], v[98:99], v[128:129] op_sel_hi:[1,0]
	v_add_f32_e32 v130, v130, v131
	v_pk_fma_f32 v[96:97], v[30:31], v[92:93], v[96:97]
	v_pk_fma_f32 v[98:99], v[32:33], v[94:95], v[98:99]
	v_add_f32_dpp v130, v130, v130 quad_perm:[1,0,3,2] row_mask:0xf bank_mask:0xf bound_ctrl:1
	v_add_f32_dpp v134, v134, v134 quad_perm:[1,0,3,2] row_mask:0xf bank_mask:0xf bound_ctrl:1
	v_pk_mul_f32 v[132:133], v[82:83], v[30:31]
	v_add_f32_dpp v130, v130, v130 quad_perm:[2,3,0,1] row_mask:0xf bank_mask:0xf bound_ctrl:1
	v_add_f32_dpp v134, v134, v134 quad_perm:[2,3,0,1] row_mask:0xf bank_mask:0xf bound_ctrl:1
	v_pk_fma_f32 v[132:133], v[84:85], v[32:33], v[132:133]
	v_add_f32_dpp v130, v130, v130 row_half_mirror row_mask:0xf bank_mask:0xf bound_ctrl:1
	v_add_f32_dpp v134, v134, v134 row_half_mirror row_mask:0xf bank_mask:0xf bound_ctrl:1
	v_add_f32_e32 v132, v132, v133
	v_add_f32_dpp v130, v130, v130 row_mirror row_mask:0xf bank_mask:0xf bound_ctrl:1
	v_add_f32_dpp v134, v134, v134 row_mirror row_mask:0xf bank_mask:0xf bound_ctrl:1
	v_cndmask_b32_e64 v44, v44, v134, s[28:29]
	v_pk_fma_f32 v[30:31], v[100:101], v[130:131], v[96:97] op_sel_hi:[1,0,1]
	v_pk_fma_f32 v[32:33], v[102:103], v[130:131], v[98:99] op_sel_hi:[1,0,1]
	ds_read_b128 v[46:49], v34 offset:25600
	ds_read_b128 v[66:69], v34 offset:27136
	ds_read2st64_b32 v[86:87], v35 offset0:99 offset1:105
	ds_read_b128 v[54:57], v34 offset:25088
	ds_read_b128 v[50:53], v34 offset:24832
	ds_read_b128 v[58:61], v34 offset:25856
	ds_read_b128 v[62:65], v34 offset:24576
	ds_read_b128 v[74:77], v34 offset:26624
	ds_read_b128 v[70:73], v34 offset:26368
	ds_read_b128 v[78:81], v34 offset:27392
	ds_read_b128 v[82:85], v34 offset:26112
	v_pk_mul_f32 v[130:131], v[30:31], v[108:109]
	v_pk_mul_f32 v[116:117], v[116:117], v[128:129] op_sel:[0,1] op_sel_hi:[1,1]
	v_pk_fma_f32 v[130:131], v[32:33], v[110:111], v[130:131]
	v_pk_mul_f32 v[118:119], v[118:119], v[128:129] op_sel:[0,1] op_sel_hi:[1,1]
	v_add_f32_e32 v130, v130, v131
	v_pk_fma_f32 v[116:117], v[30:31], v[112:113], v[116:117]
	v_pk_fma_f32 v[118:119], v[32:33], v[114:115], v[118:119]
	v_add_f32_dpp v130, v130, v130 quad_perm:[1,0,3,2] row_mask:0xf bank_mask:0xf bound_ctrl:1
	v_add_f32_dpp v132, v132, v132 quad_perm:[1,0,3,2] row_mask:0xf bank_mask:0xf bound_ctrl:1
	v_pk_mul_f32 v[134:135], v[104:105], v[30:31]
	v_add_f32_dpp v130, v130, v130 quad_perm:[2,3,0,1] row_mask:0xf bank_mask:0xf bound_ctrl:1
	v_add_f32_dpp v132, v132, v132 quad_perm:[2,3,0,1] row_mask:0xf bank_mask:0xf bound_ctrl:1
	v_pk_fma_f32 v[134:135], v[106:107], v[32:33], v[134:135]
	v_add_f32_dpp v130, v130, v130 row_half_mirror row_mask:0xf bank_mask:0xf bound_ctrl:1
	v_add_f32_dpp v132, v132, v132 row_half_mirror row_mask:0xf bank_mask:0xf bound_ctrl:1
	v_add_f32_e32 v134, v134, v135
	v_add_f32_dpp v130, v130, v130 row_mirror row_mask:0xf bank_mask:0xf bound_ctrl:1
	v_add_f32_dpp v132, v132, v132 row_mirror row_mask:0xf bank_mask:0xf bound_ctrl:1
	v_cndmask_b32_e64 v44, v44, v132, s[30:31]
	v_pk_fma_f32 v[30:31], v[120:121], v[130:131], v[116:117] op_sel_hi:[1,0,1]
	v_pk_fma_f32 v[32:33], v[122:123], v[130:131], v[118:119] op_sel_hi:[1,0,1]
	s_waitcnt lgkmcnt(0)
; __device__ __forceinline__ void phase_scan(const Params& P, char* smem) {
;     ...
;     for (int j = 0; j < 16; ++j) {
;       if (j + 1 < 16) {
;         SCAN_LOADB(j + 1, (j + 1) & 1)
;       }
;       __builtin_amdgcn_sched_barrier(0);
; #pragma unroll
;       for (int u = 0; u < 2; ++u) {
;         const int sl2 = j & 1;
;         const int st = j * 2 + u;
;         const f32x4 a4 = La[sl2][u], b4 = Lb[sl2][u], w4 = Lw[sl2][u], kd = Lk[sl2][u], r4 = Lr[sl2][u];
;         const float vv = Lv[sl2][u];
;         f32x2 p = S01 * a4.xy;
;         p = S23 * a4.zw + p;
;         float sa = p.x + p.y;
;         sa += dppf(sa, 0); yprev += dppf(yprev, 0);
;         sa += dppf(sa, 1); yprev += dppf(yprev, 1);
;         sa += dppf(sa, 2); yprev += dppf(yprev, 2);
;         sa += dppf(sa, 3); yprev += dppf(yprev, 3);
;         if (st >= 1 && st <= 16) ykeep0 = (kq == st - 1) ? yprev : ykeep0;
;         if (st >= 17) ykeep1 = (kq == st - 17) ? yprev : ykeep1;
;         const f32x2 sa2 = (f32x2){sa, sa}, vv2 = (f32x2){vv, vv};
;         const f32x2 t01 = sa2 * b4.xy + vv2 * kd.xy;
;         const f32x2 t23 = sa2 * b4.zw + vv2 * kd.zw;
;         S01 = S01 * w4.xy + t01;
;         S23 = S23 * w4.zw + t23;
;         f32x2 q = S01 * r4.xy;
;         q = S23 * r4.zw + q;
;         yprev = q.x + q.y;
;       }
	v_pk_mul_f32 v[130:131], v[30:31], v[46:47]
	v_pk_mul_f32 v[54:55], v[54:55], v[86:87] op_sel_hi:[1,0]
	v_pk_fma_f32 v[130:131], v[32:33], v[48:49], v[130:131]
	v_pk_mul_f32 v[56:57], v[56:57], v[86:87] op_sel_hi:[1,0]
	v_add_f32_e32 v130, v130, v131
	v_pk_fma_f32 v[54:55], v[30:31], v[50:51], v[54:55]
	v_pk_fma_f32 v[56:57], v[32:33], v[52:53], v[56:57]
	v_add_f32_dpp v130, v130, v130 quad_perm:[1,0,3,2] row_mask:0xf bank_mask:0xf bound_ctrl:1
	v_add_f32_dpp v134, v134, v134 quad_perm:[1,0,3,2] row_mask:0xf bank_mask:0xf bound_ctrl:1
	v_pk_mul_f32 v[132:133], v[124:125], v[30:31]
	v_add_f32_dpp v130, v130, v130 quad_perm:[2,3,0,1] row_mask:0xf bank_mask:0xf bound_ctrl:1
	v_add_f32_dpp v134, v134, v134 quad_perm:[2,3,0,1] row_mask:0xf bank_mask:0xf bound_ctrl:1
	v_pk_fma_f32 v[132:133], v[126:127], v[32:33], v[132:133]
	v_add_f32_dpp v130, v130, v130 row_half_mirror row_mask:0xf bank_mask:0xf bound_ctrl:1
	v_add_f32_dpp v134, v134, v134 row_half_mirror row_mask:0xf bank_mask:0xf bound_ctrl:1
	v_add_f32_e32 v132, v132, v133
	v_add_f32_dpp v130, v130, v130 row_mirror row_mask:0xf bank_mask:0xf bound_ctrl:1
	v_add_f32_dpp v134, v134, v134 row_mirror row_mask:0xf bank_mask:0xf bound_ctrl:1
	v_cndmask_b32_e64 v44, v44, v134, s[34:35]
	v_pk_fma_f32 v[30:31], v[58:59], v[130:131], v[54:55] op_sel_hi:[1,0,1]
	v_pk_fma_f32 v[32:33], v[60:61], v[130:131], v[56:57] op_sel_hi:[1,0,1]
	ds_read_b128 v[88:91], v34 offset:28672
	ds_read_b128 v[108:111], v34 offset:30208
	ds_read2st64_b32 v[128:129], v35 offset0:111 offset1:117
	ds_read_b128 v[96:99], v34 offset:28160
	ds_read_b128 v[92:95], v34 offset:27904
	ds_read_b128 v[100:103], v34 offset:28928
	ds_read_b128 v[104:107], v34 offset:27648
	ds_read_b128 v[116:119], v34 offset:29696
	ds_read_b128 v[112:115], v34 offset:29440
	ds_read_b128 v[120:123], v34 offset:30464
	ds_read_b128 v[124:127], v34 offset:29184
	v_pk_mul_f32 v[130:131], v[30:31], v[66:67]
	v_pk_mul_f32 v[74:75], v[74:75], v[86:87] op_sel:[0,1] op_sel_hi:[1,1]
	v_pk_fma_f32 v[130:131], v[32:33], v[68:69], v[130:131]
	v_pk_mul_f32 v[76:77], v[76:77], v[86:87] op_sel:[0,1] op_sel_hi:[1,1]
	v_add_f32_e32 v130, v130, v131
	v_pk_fma_f32 v[74:75], v[30:31], v[70:71], v[74:75]
	v_pk_fma_f32 v[76:77], v[32:33], v[72:73], v[76:77]
	v_add_f32_dpp v130, v130, v130 quad_perm:[1,0,3,2] row_mask:0xf bank_mask:0xf bound_ctrl:1
	v_add_f32_dpp v132, v132, v132 quad_perm:[1,0,3,2] row_mask:0xf bank_mask:0xf bound_ctrl:1
	v_pk_mul_f32 v[134:135], v[62:63], v[30:31]
	v_add_f32_dpp v130, v130, v130 quad_perm:[2,3,0,1] row_mask:0xf bank_mask:0xf bound_ctrl:1
	v_add_f32_dpp v132, v132, v132 quad_perm:[2,3,0,1] row_mask:0xf bank_mask:0xf bound_ctrl:1
	v_pk_fma_f32 v[134:135], v[64:65], v[32:33], v[134:135]
	v_add_f32_dpp v130, v130, v130 row_half_mirror row_mask:0xf bank_mask:0xf bound_ctrl:1
	v_add_f32_dpp v132, v132, v132 row_half_mirror row_mask:0xf bank_mask:0xf bound_ctrl:1
	v_add_f32_e32 v134, v134, v135
	v_add_f32_dpp v130, v130, v130 row_mirror row_mask:0xf bank_mask:0xf bound_ctrl:1
	v_add_f32_dpp v132, v132, v132 row_mirror row_mask:0xf bank_mask:0xf bound_ctrl:1
	v_cndmask_b32_e64 v44, v44, v132, s[0:1]
	v_pk_fma_f32 v[30:31], v[78:79], v[130:131], v[74:75] op_sel_hi:[1,0,1]
	v_pk_fma_f32 v[32:33], v[80:81], v[130:131], v[76:77] op_sel_hi:[1,0,1]
	s_waitcnt lgkmcnt(0)
	v_pk_mul_f32 v[130:131], v[30:31], v[88:89]
	v_pk_mul_f32 v[96:97], v[96:97], v[128:129] op_sel_hi:[1,0]
	v_pk_fma_f32 v[130:131], v[32:33], v[90:91], v[130:131]
	v_pk_mul_f32 v[98:99], v[98:99], v[128:129] op_sel_hi:[1,0]
	v_add_f32_e32 v130, v130, v131
	v_pk_fma_f32 v[96:97], v[30:31], v[92:93], v[96:97]
	v_pk_fma_f32 v[98:99], v[32:33], v[94:95], v[98:99]
	v_add_f32_dpp v130, v130, v130 quad_perm:[1,0,3,2] row_mask:0xf bank_mask:0xf bound_ctrl:1
	v_add_f32_dpp v134, v134, v134 quad_perm:[1,0,3,2] row_mask:0xf bank_mask:0xf bound_ctrl:1
	v_pk_mul_f32 v[132:133], v[82:83], v[30:31]
	v_add_f32_dpp v130, v130, v130 quad_perm:[2,3,0,1] row_mask:0xf bank_mask:0xf bound_ctrl:1
	v_add_f32_dpp v134, v134, v134 quad_perm:[2,3,0,1] row_mask:0xf bank_mask:0xf bound_ctrl:1
	v_pk_fma_f32 v[132:133], v[84:85], v[32:33], v[132:133]
	v_add_f32_dpp v130, v130, v130 row_half_mirror row_mask:0xf bank_mask:0xf bound_ctrl:1
	v_add_f32_dpp v134, v134, v134 row_half_mirror row_mask:0xf bank_mask:0xf bound_ctrl:1
	v_add_f32_e32 v132, v132, v133
	v_add_f32_dpp v130, v130, v130 row_mirror row_mask:0xf bank_mask:0xf bound_ctrl:1
	v_add_f32_dpp v134, v134, v134 row_mirror row_mask:0xf bank_mask:0xf bound_ctrl:1
	v_cndmask_b32_e64 v45, 0, v134, s[36:37]
	v_pk_fma_f32 v[30:31], v[100:101], v[130:131], v[96:97] op_sel_hi:[1,0,1]
	v_pk_fma_f32 v[32:33], v[102:103], v[130:131], v[98:99] op_sel_hi:[1,0,1]
	ds_read_b128 v[46:49], v34 offset:31744
	ds_read_b128 v[66:69], v34 offset:33280
	ds_read2st64_b32 v[86:87], v35 offset0:123 offset1:129
	ds_read_b128 v[54:57], v34 offset:31232
	ds_read_b128 v[50:53], v34 offset:30976
	ds_read_b128 v[58:61], v34 offset:32000
	ds_read_b128 v[62:65], v34 offset:30720
	ds_read_b128 v[74:77], v34 offset:32768
	ds_read_b128 v[70:73], v34 offset:32512
	ds_read_b128 v[78:81], v34 offset:33536
	ds_read_b128 v[82:85], v34 offset:32256
	v_pk_mul_f32 v[130:131], v[30:31], v[108:109]
	v_pk_mul_f32 v[116:117], v[116:117], v[128:129] op_sel:[0,1] op_sel_hi:[1,1]
	v_pk_fma_f32 v[130:131], v[32:33], v[110:111], v[130:131]
	v_pk_mul_f32 v[118:119], v[118:119], v[128:129] op_sel:[0,1] op_sel_hi:[1,1]
	v_add_f32_e32 v130, v130, v131
	v_pk_fma_f32 v[116:117], v[30:31], v[112:113], v[116:117]
	v_pk_fma_f32 v[118:119], v[32:33], v[114:115], v[118:119]
	v_add_f32_dpp v130, v130, v130 quad_perm:[1,0,3,2] row_mask:0xf bank_mask:0xf bound_ctrl:1
	v_add_f32_dpp v132, v132, v132 quad_perm:[1,0,3,2] row_mask:0xf bank_mask:0xf bound_ctrl:1
	v_pk_mul_f32 v[134:135], v[104:105], v[30:31]
	v_add_f32_dpp v130, v130, v130 quad_perm:[2,3,0,1] row_mask:0xf bank_mask:0xf bound_ctrl:1
	v_add_f32_dpp v132, v132, v132 quad_perm:[2,3,0,1] row_mask:0xf bank_mask:0xf bound_ctrl:1
	v_pk_fma_f32 v[134:135], v[106:107], v[32:33], v[134:135]
	v_add_f32_dpp v130, v130, v130 row_half_mirror row_mask:0xf bank_mask:0xf bound_ctrl:1
	v_add_f32_dpp v132, v132, v132 row_half_mirror row_mask:0xf bank_mask:0xf bound_ctrl:1
	v_add_f32_e32 v134, v134, v135
	v_add_f32_dpp v130, v130, v130 row_mirror row_mask:0xf bank_mask:0xf bound_ctrl:1
	v_add_f32_dpp v132, v132, v132 row_mirror row_mask:0xf bank_mask:0xf bound_ctrl:1
	v_cndmask_b32_e64 v45, v45, v132, s[4:5]
	v_pk_fma_f32 v[30:31], v[120:121], v[130:131], v[116:117] op_sel_hi:[1,0,1]
	v_pk_fma_f32 v[32:33], v[122:123], v[130:131], v[118:119] op_sel_hi:[1,0,1]
	s_waitcnt lgkmcnt(0)
; __device__ __forceinline__ void phase_scan(const Params& P, char* smem) {
;     ...
;     for (int j = 0; j < 16; ++j) {
;       if (j + 1 < 16) {
;         SCAN_LOADB(j + 1, (j + 1) & 1)
;       }
;       __builtin_amdgcn_sched_barrier(0);
; #pragma unroll
;       for (int u = 0; u < 2; ++u) {
;         const int sl2 = j & 1;
;         const int st = j * 2 + u;
;         const f32x4 a4 = La[sl2][u], b4 = Lb[sl2][u], w4 = Lw[sl2][u], kd = Lk[sl2][u], r4 = Lr[sl2][u];
;         const float vv = Lv[sl2][u];
;         f32x2 p = S01 * a4.xy;
;         p = S23 * a4.zw + p;
;         float sa = p.x + p.y;
;         sa += dppf(sa, 0); yprev += dppf(yprev, 0);
;         sa += dppf(sa, 1); yprev += dppf(yprev, 1);
;         sa += dppf(sa, 2); yprev += dppf(yprev, 2);
;         sa += dppf(sa, 3); yprev += dppf(yprev, 3);
;         if (st >= 1 && st <= 16) ykeep0 = (kq == st - 1) ? yprev : ykeep0;
;         if (st >= 17) ykeep1 = (kq == st - 17) ? yprev : ykeep1;
;         const f32x2 sa2 = (f32x2){sa, sa}, vv2 = (f32x2){vv, vv};
;         const f32x2 t01 = sa2 * b4.xy + vv2 * kd.xy;
;         const f32x2 t23 = sa2 * b4.zw + vv2 * kd.zw;
;         S01 = S01 * w4.xy + t01;
;         S23 = S23 * w4.zw + t23;
;         f32x2 q = S01 * r4.xy;
;         q = S23 * r4.zw + q;
;         yprev = q.x + q.y;
;       }
	v_pk_mul_f32 v[130:131], v[30:31], v[46:47]
	v_pk_mul_f32 v[54:55], v[54:55], v[86:87] op_sel_hi:[1,0]
	v_pk_fma_f32 v[130:131], v[32:33], v[48:49], v[130:131]
	v_pk_mul_f32 v[56:57], v[56:57], v[86:87] op_sel_hi:[1,0]
	v_add_f32_e32 v130, v130, v131
	v_pk_fma_f32 v[54:55], v[30:31], v[50:51], v[54:55]
	v_pk_fma_f32 v[56:57], v[32:33], v[52:53], v[56:57]
	v_add_f32_dpp v130, v130, v130 quad_perm:[1,0,3,2] row_mask:0xf bank_mask:0xf bound_ctrl:1
	v_add_f32_dpp v134, v134, v134 quad_perm:[1,0,3,2] row_mask:0xf bank_mask:0xf bound_ctrl:1
	v_pk_mul_f32 v[132:133], v[124:125], v[30:31]
	v_add_f32_dpp v130, v130, v130 quad_perm:[2,3,0,1] row_mask:0xf bank_mask:0xf bound_ctrl:1
	v_add_f32_dpp v134, v134, v134 quad_perm:[2,3,0,1] row_mask:0xf bank_mask:0xf bound_ctrl:1
	v_pk_fma_f32 v[132:133], v[126:127], v[32:33], v[132:133]
	v_add_f32_dpp v130, v130, v130 row_half_mirror row_mask:0xf bank_mask:0xf bound_ctrl:1
	v_add_f32_dpp v134, v134, v134 row_half_mirror row_mask:0xf bank_mask:0xf bound_ctrl:1
	v_add_f32_e32 v132, v132, v133
	v_add_f32_dpp v130, v130, v130 row_mirror row_mask:0xf bank_mask:0xf bound_ctrl:1
	v_add_f32_dpp v134, v134, v134 row_mirror row_mask:0xf bank_mask:0xf bound_ctrl:1
	v_cndmask_b32_e64 v45, v45, v134, s[6:7]
	v_pk_fma_f32 v[30:31], v[58:59], v[130:131], v[54:55] op_sel_hi:[1,0,1]
	v_pk_fma_f32 v[32:33], v[60:61], v[130:131], v[56:57] op_sel_hi:[1,0,1]
	ds_read_b128 v[88:91], v34 offset:34816
	ds_read_b128 v[108:111], v34 offset:36352
	ds_read2st64_b32 v[128:129], v35 offset0:135 offset1:141
	ds_read_b128 v[96:99], v34 offset:34304
	ds_read_b128 v[92:95], v34 offset:34048
	ds_read_b128 v[100:103], v34 offset:35072
	ds_read_b128 v[104:107], v34 offset:33792
	ds_read_b128 v[116:119], v34 offset:35840
	ds_read_b128 v[112:115], v34 offset:35584
	ds_read_b128 v[120:123], v34 offset:36608
	ds_read_b128 v[124:127], v34 offset:35328
	v_pk_mul_f32 v[130:131], v[30:31], v[66:67]
	v_pk_mul_f32 v[74:75], v[74:75], v[86:87] op_sel:[0,1] op_sel_hi:[1,1]
	v_pk_fma_f32 v[130:131], v[32:33], v[68:69], v[130:131]
	v_pk_mul_f32 v[76:77], v[76:77], v[86:87] op_sel:[0,1] op_sel_hi:[1,1]
	v_add_f32_e32 v130, v130, v131
	v_pk_fma_f32 v[74:75], v[30:31], v[70:71], v[74:75]
	v_pk_fma_f32 v[76:77], v[32:33], v[72:73], v[76:77]
	v_add_f32_dpp v130, v130, v130 quad_perm:[1,0,3,2] row_mask:0xf bank_mask:0xf bound_ctrl:1
	v_add_f32_dpp v132, v132, v132 quad_perm:[1,0,3,2] row_mask:0xf bank_mask:0xf bound_ctrl:1
	v_pk_mul_f32 v[134:135], v[62:63], v[30:31]
	v_add_f32_dpp v130, v130, v130 quad_perm:[2,3,0,1] row_mask:0xf bank_mask:0xf bound_ctrl:1
	v_add_f32_dpp v132, v132, v132 quad_perm:[2,3,0,1] row_mask:0xf bank_mask:0xf bound_ctrl:1
	v_pk_fma_f32 v[134:135], v[64:65], v[32:33], v[134:135]
	v_add_f32_dpp v130, v130, v130 row_half_mirror row_mask:0xf bank_mask:0xf bound_ctrl:1
	v_add_f32_dpp v132, v132, v132 row_half_mirror row_mask:0xf bank_mask:0xf bound_ctrl:1
	v_add_f32_e32 v134, v134, v135
	v_add_f32_dpp v130, v130, v130 row_mirror row_mask:0xf bank_mask:0xf bound_ctrl:1
	v_add_f32_dpp v132, v132, v132 row_mirror row_mask:0xf bank_mask:0xf bound_ctrl:1
	v_cndmask_b32_e64 v45, v45, v132, s[8:9]
	v_pk_fma_f32 v[30:31], v[78:79], v[130:131], v[74:75] op_sel_hi:[1,0,1]
	v_pk_fma_f32 v[32:33], v[80:81], v[130:131], v[76:77] op_sel_hi:[1,0,1]
	s_waitcnt lgkmcnt(0)
	v_pk_mul_f32 v[130:131], v[30:31], v[88:89]
	v_pk_mul_f32 v[96:97], v[96:97], v[128:129] op_sel_hi:[1,0]
	v_pk_fma_f32 v[130:131], v[32:33], v[90:91], v[130:131]
	v_pk_mul_f32 v[98:99], v[98:99], v[128:129] op_sel_hi:[1,0]
	v_add_f32_e32 v130, v130, v131
	v_pk_fma_f32 v[96:97], v[30:31], v[92:93], v[96:97]
	v_pk_fma_f32 v[98:99], v[32:33], v[94:95], v[98:99]
	v_add_f32_dpp v130, v130, v130 quad_perm:[1,0,3,2] row_mask:0xf bank_mask:0xf bound_ctrl:1
	v_add_f32_dpp v134, v134, v134 quad_perm:[1,0,3,2] row_mask:0xf bank_mask:0xf bound_ctrl:1
	v_pk_mul_f32 v[132:133], v[82:83], v[30:31]
	v_add_f32_dpp v130, v130, v130 quad_perm:[2,3,0,1] row_mask:0xf bank_mask:0xf bound_ctrl:1
	v_add_f32_dpp v134, v134, v134 quad_perm:[2,3,0,1] row_mask:0xf bank_mask:0xf bound_ctrl:1
	v_pk_fma_f32 v[132:133], v[84:85], v[32:33], v[132:133]
	v_add_f32_dpp v130, v130, v130 row_half_mirror row_mask:0xf bank_mask:0xf bound_ctrl:1
	v_add_f32_dpp v134, v134, v134 row_half_mirror row_mask:0xf bank_mask:0xf bound_ctrl:1
	v_add_f32_e32 v132, v132, v133
	v_add_f32_dpp v130, v130, v130 row_mirror row_mask:0xf bank_mask:0xf bound_ctrl:1
	v_add_f32_dpp v134, v134, v134 row_mirror row_mask:0xf bank_mask:0xf bound_ctrl:1
	v_cndmask_b32_e64 v45, v45, v134, s[12:13]
	v_pk_fma_f32 v[30:31], v[100:101], v[130:131], v[96:97] op_sel_hi:[1,0,1]
	v_pk_fma_f32 v[32:33], v[102:103], v[130:131], v[98:99] op_sel_hi:[1,0,1]
	ds_read_b128 v[46:49], v34 offset:37888
	ds_read_b128 v[66:69], v34 offset:39424
	ds_read2st64_b32 v[86:87], v35 offset0:147 offset1:153
	ds_read_b128 v[54:57], v34 offset:37376
	ds_read_b128 v[50:53], v34 offset:37120
	ds_read_b128 v[58:61], v34 offset:38144
	ds_read_b128 v[62:65], v34 offset:36864
	ds_read_b128 v[74:77], v34 offset:38912
	ds_read_b128 v[70:73], v34 offset:38656
	ds_read_b128 v[78:81], v34 offset:39680
	ds_read_b128 v[82:85], v34 offset:38400
	v_pk_mul_f32 v[130:131], v[30:31], v[108:109]
	v_pk_mul_f32 v[116:117], v[116:117], v[128:129] op_sel:[0,1] op_sel_hi:[1,1]
	v_pk_fma_f32 v[130:131], v[32:33], v[110:111], v[130:131]
	v_pk_mul_f32 v[118:119], v[118:119], v[128:129] op_sel:[0,1] op_sel_hi:[1,1]
	v_add_f32_e32 v130, v130, v131
	v_pk_fma_f32 v[116:117], v[30:31], v[112:113], v[116:117]
	v_pk_fma_f32 v[118:119], v[32:33], v[114:115], v[118:119]
	v_add_f32_dpp v130, v130, v130 quad_perm:[1,0,3,2] row_mask:0xf bank_mask:0xf bound_ctrl:1
	v_add_f32_dpp v132, v132, v132 quad_perm:[1,0,3,2] row_mask:0xf bank_mask:0xf bound_ctrl:1
	v_pk_mul_f32 v[134:135], v[104:105], v[30:31]
	v_add_f32_dpp v130, v130, v130 quad_perm:[2,3,0,1] row_mask:0xf bank_mask:0xf bound_ctrl:1
	v_add_f32_dpp v132, v132, v132 quad_perm:[2,3,0,1] row_mask:0xf bank_mask:0xf bound_ctrl:1
	v_pk_fma_f32 v[134:135], v[106:107], v[32:33], v[134:135]
	v_add_f32_dpp v130, v130, v130 row_half_mirror row_mask:0xf bank_mask:0xf bound_ctrl:1
	v_add_f32_dpp v132, v132, v132 row_half_mirror row_mask:0xf bank_mask:0xf bound_ctrl:1
	v_add_f32_e32 v134, v134, v135
	v_add_f32_dpp v130, v130, v130 row_mirror row_mask:0xf bank_mask:0xf bound_ctrl:1
	v_add_f32_dpp v132, v132, v132 row_mirror row_mask:0xf bank_mask:0xf bound_ctrl:1
	v_cndmask_b32_e64 v45, v45, v132, s[14:15]
	v_pk_fma_f32 v[30:31], v[120:121], v[130:131], v[116:117] op_sel_hi:[1,0,1]
	v_pk_fma_f32 v[32:33], v[122:123], v[130:131], v[118:119] op_sel_hi:[1,0,1]
	s_waitcnt lgkmcnt(0)
; __device__ __forceinline__ void phase_scan(const Params& P, char* smem) {
;     ...
;     for (int j = 0; j < 16; ++j) {
;       if (j + 1 < 16) {
;         SCAN_LOADB(j + 1, (j + 1) & 1)
;       }
;       __builtin_amdgcn_sched_barrier(0);
; #pragma unroll
;       for (int u = 0; u < 2; ++u) {
;         const int sl2 = j & 1;
;         const int st = j * 2 + u;
;         const f32x4 a4 = La[sl2][u], b4 = Lb[sl2][u], w4 = Lw[sl2][u], kd = Lk[sl2][u], r4 = Lr[sl2][u];
;         const float vv = Lv[sl2][u];
;         f32x2 p = S01 * a4.xy;
;         p = S23 * a4.zw + p;
;         float sa = p.x + p.y;
;         sa += dppf(sa, 0); yprev += dppf(yprev, 0);
;         sa += dppf(sa, 1); yprev += dppf(yprev, 1);
;         sa += dppf(sa, 2); yprev += dppf(yprev, 2);
;         sa += dppf(sa, 3); yprev += dppf(yprev, 3);
;         if (st >= 1 && st <= 16) ykeep0 = (kq == st - 1) ? yprev : ykeep0;
;         if (st >= 17) ykeep1 = (kq == st - 17) ? yprev : ykeep1;
;         const f32x2 sa2 = (f32x2){sa, sa}, vv2 = (f32x2){vv, vv};
;         const f32x2 t01 = sa2 * b4.xy + vv2 * kd.xy;
;         const f32x2 t23 = sa2 * b4.zw + vv2 * kd.zw;
;         S01 = S01 * w4.xy + t01;
;         S23 = S23 * w4.zw + t23;
;         f32x2 q = S01 * r4.xy;
;         q = S23 * r4.zw + q;
;         yprev = q.x + q.y;
;       }
	v_pk_mul_f32 v[130:131], v[30:31], v[46:47]
	v_pk_mul_f32 v[54:55], v[54:55], v[86:87] op_sel_hi:[1,0]
	v_pk_fma_f32 v[130:131], v[32:33], v[48:49], v[130:131]
	v_pk_mul_f32 v[56:57], v[56:57], v[86:87] op_sel_hi:[1,0]
	v_add_f32_e32 v130, v130, v131
	v_pk_fma_f32 v[54:55], v[30:31], v[50:51], v[54:55]
	v_pk_fma_f32 v[56:57], v[32:33], v[52:53], v[56:57]
	v_add_f32_dpp v130, v130, v130 quad_perm:[1,0,3,2] row_mask:0xf bank_mask:0xf bound_ctrl:1
	v_add_f32_dpp v134, v134, v134 quad_perm:[1,0,3,2] row_mask:0xf bank_mask:0xf bound_ctrl:1
	v_pk_mul_f32 v[132:133], v[124:125], v[30:31]
	v_add_f32_dpp v130, v130, v130 quad_perm:[2,3,0,1] row_mask:0xf bank_mask:0xf bound_ctrl:1
	v_add_f32_dpp v134, v134, v134 quad_perm:[2,3,0,1] row_mask:0xf bank_mask:0xf bound_ctrl:1
	v_pk_fma_f32 v[132:133], v[126:127], v[32:33], v[132:133]
	v_add_f32_dpp v130, v130, v130 row_half_mirror row_mask:0xf bank_mask:0xf bound_ctrl:1
	v_add_f32_dpp v134, v134, v134 row_half_mirror row_mask:0xf bank_mask:0xf bound_ctrl:1
	v_add_f32_e32 v132, v132, v133
	v_add_f32_dpp v130, v130, v130 row_mirror row_mask:0xf bank_mask:0xf bound_ctrl:1
	v_add_f32_dpp v134, v134, v134 row_mirror row_mask:0xf bank_mask:0xf bound_ctrl:1
	v_cndmask_b32_e64 v45, v45, v134, s[16:17]
	v_pk_fma_f32 v[30:31], v[58:59], v[130:131], v[54:55] op_sel_hi:[1,0,1]
	v_pk_fma_f32 v[32:33], v[60:61], v[130:131], v[56:57] op_sel_hi:[1,0,1]
	ds_read_b128 v[88:91], v34 offset:40960
	ds_read_b128 v[108:111], v34 offset:42496
	ds_read2st64_b32 v[128:129], v35 offset0:159 offset1:165
	ds_read_b128 v[96:99], v34 offset:40448
	ds_read_b128 v[92:95], v34 offset:40192
	ds_read_b128 v[100:103], v34 offset:41216
	ds_read_b128 v[104:107], v34 offset:39936
	ds_read_b128 v[116:119], v34 offset:41984
	ds_read_b128 v[112:115], v34 offset:41728
	ds_read_b128 v[120:123], v34 offset:42752
	ds_read_b128 v[124:127], v34 offset:41472
	v_pk_mul_f32 v[130:131], v[30:31], v[66:67]
	v_pk_mul_f32 v[74:75], v[74:75], v[86:87] op_sel:[0,1] op_sel_hi:[1,1]
	v_pk_fma_f32 v[130:131], v[32:33], v[68:69], v[130:131]
	v_pk_mul_f32 v[76:77], v[76:77], v[86:87] op_sel:[0,1] op_sel_hi:[1,1]
	v_add_f32_e32 v130, v130, v131
	v_pk_fma_f32 v[74:75], v[30:31], v[70:71], v[74:75]
	v_pk_fma_f32 v[76:77], v[32:33], v[72:73], v[76:77]
	v_add_f32_dpp v130, v130, v130 quad_perm:[1,0,3,2] row_mask:0xf bank_mask:0xf bound_ctrl:1
	v_add_f32_dpp v132, v132, v132 quad_perm:[1,0,3,2] row_mask:0xf bank_mask:0xf bound_ctrl:1
	v_pk_mul_f32 v[134:135], v[62:63], v[30:31]
	v_add_f32_dpp v130, v130, v130 quad_perm:[2,3,0,1] row_mask:0xf bank_mask:0xf bound_ctrl:1
	v_add_f32_dpp v132, v132, v132 quad_perm:[2,3,0,1] row_mask:0xf bank_mask:0xf bound_ctrl:1
	v_pk_fma_f32 v[134:135], v[64:65], v[32:33], v[134:135]
	v_add_f32_dpp v130, v130, v130 row_half_mirror row_mask:0xf bank_mask:0xf bound_ctrl:1
	v_add_f32_dpp v132, v132, v132 row_half_mirror row_mask:0xf bank_mask:0xf bound_ctrl:1
	v_add_f32_e32 v134, v134, v135
	v_add_f32_dpp v130, v130, v130 row_mirror row_mask:0xf bank_mask:0xf bound_ctrl:1
	v_add_f32_dpp v132, v132, v132 row_mirror row_mask:0xf bank_mask:0xf bound_ctrl:1
	v_cndmask_b32_e64 v45, v45, v132, s[18:19]
	v_pk_fma_f32 v[30:31], v[78:79], v[130:131], v[74:75] op_sel_hi:[1,0,1]
	v_pk_fma_f32 v[32:33], v[80:81], v[130:131], v[76:77] op_sel_hi:[1,0,1]
	s_waitcnt lgkmcnt(0)
	v_pk_mul_f32 v[130:131], v[30:31], v[88:89]
	v_pk_mul_f32 v[96:97], v[96:97], v[128:129] op_sel_hi:[1,0]
	v_pk_fma_f32 v[130:131], v[32:33], v[90:91], v[130:131]
	v_pk_mul_f32 v[98:99], v[98:99], v[128:129] op_sel_hi:[1,0]
	v_add_f32_e32 v130, v130, v131
	v_pk_fma_f32 v[96:97], v[30:31], v[92:93], v[96:97]
	v_pk_fma_f32 v[98:99], v[32:33], v[94:95], v[98:99]
	v_add_f32_dpp v130, v130, v130 quad_perm:[1,0,3,2] row_mask:0xf bank_mask:0xf bound_ctrl:1
	v_add_f32_dpp v134, v134, v134 quad_perm:[1,0,3,2] row_mask:0xf bank_mask:0xf bound_ctrl:1
	v_pk_mul_f32 v[132:133], v[82:83], v[30:31]
	v_add_f32_dpp v130, v130, v130 quad_perm:[2,3,0,1] row_mask:0xf bank_mask:0xf bound_ctrl:1
	v_add_f32_dpp v134, v134, v134 quad_perm:[2,3,0,1] row_mask:0xf bank_mask:0xf bound_ctrl:1
	v_pk_fma_f32 v[132:133], v[84:85], v[32:33], v[132:133]
	v_add_f32_dpp v130, v130, v130 row_half_mirror row_mask:0xf bank_mask:0xf bound_ctrl:1
	v_add_f32_dpp v134, v134, v134 row_half_mirror row_mask:0xf bank_mask:0xf bound_ctrl:1
	v_add_f32_e32 v132, v132, v133
	v_add_f32_dpp v130, v130, v130 row_mirror row_mask:0xf bank_mask:0xf bound_ctrl:1
	v_add_f32_dpp v134, v134, v134 row_mirror row_mask:0xf bank_mask:0xf bound_ctrl:1
	v_cndmask_b32_e64 v45, v45, v134, s[20:21]
	v_pk_fma_f32 v[30:31], v[100:101], v[130:131], v[96:97] op_sel_hi:[1,0,1]
	v_pk_fma_f32 v[32:33], v[102:103], v[130:131], v[98:99] op_sel_hi:[1,0,1]
	ds_read_b128 v[46:49], v34 offset:44032
	ds_read_b128 v[66:69], v34 offset:45568
	ds_read2st64_b32 v[86:87], v35 offset0:171 offset1:177
	ds_read_b128 v[54:57], v34 offset:43520
	ds_read_b128 v[50:53], v34 offset:43264
	ds_read_b128 v[58:61], v34 offset:44288
	ds_read_b128 v[62:65], v34 offset:43008
	ds_read_b128 v[74:77], v34 offset:45056
	ds_read_b128 v[70:73], v34 offset:44800
	ds_read_b128 v[78:81], v34 offset:45824
	ds_read_b128 v[82:85], v34 offset:44544
	v_pk_mul_f32 v[130:131], v[30:31], v[108:109]
	v_pk_mul_f32 v[116:117], v[116:117], v[128:129] op_sel:[0,1] op_sel_hi:[1,1]
	v_pk_fma_f32 v[130:131], v[32:33], v[110:111], v[130:131]
	v_pk_mul_f32 v[118:119], v[118:119], v[128:129] op_sel:[0,1] op_sel_hi:[1,1]
	v_add_f32_e32 v130, v130, v131
	v_pk_fma_f32 v[116:117], v[30:31], v[112:113], v[116:117]
	v_pk_fma_f32 v[118:119], v[32:33], v[114:115], v[118:119]
	v_add_f32_dpp v130, v130, v130 quad_perm:[1,0,3,2] row_mask:0xf bank_mask:0xf bound_ctrl:1
	v_add_f32_dpp v132, v132, v132 quad_perm:[1,0,3,2] row_mask:0xf bank_mask:0xf bound_ctrl:1
	v_pk_mul_f32 v[134:135], v[104:105], v[30:31]
	v_add_f32_dpp v130, v130, v130 quad_perm:[2,3,0,1] row_mask:0xf bank_mask:0xf bound_ctrl:1
	v_add_f32_dpp v132, v132, v132 quad_perm:[2,3,0,1] row_mask:0xf bank_mask:0xf bound_ctrl:1
	v_pk_fma_f32 v[134:135], v[106:107], v[32:33], v[134:135]
	v_add_f32_dpp v130, v130, v130 row_half_mirror row_mask:0xf bank_mask:0xf bound_ctrl:1
	v_add_f32_dpp v132, v132, v132 row_half_mirror row_mask:0xf bank_mask:0xf bound_ctrl:1
	v_add_f32_e32 v134, v134, v135
	v_add_f32_dpp v130, v130, v130 row_mirror row_mask:0xf bank_mask:0xf bound_ctrl:1
	v_add_f32_dpp v132, v132, v132 row_mirror row_mask:0xf bank_mask:0xf bound_ctrl:1
	v_cndmask_b32_e64 v45, v45, v132, s[22:23]
	v_pk_fma_f32 v[30:31], v[120:121], v[130:131], v[116:117] op_sel_hi:[1,0,1]
	v_pk_fma_f32 v[32:33], v[122:123], v[130:131], v[118:119] op_sel_hi:[1,0,1]
	s_waitcnt lgkmcnt(0)
; __device__ __forceinline__ void phase_scan(const Params& P, char* smem) {
;     ...
;     for (int j = 0; j < 16; ++j) {
;       if (j + 1 < 16) {
;         SCAN_LOADB(j + 1, (j + 1) & 1)
;       }
;       __builtin_amdgcn_sched_barrier(0);
; #pragma unroll
;       for (int u = 0; u < 2; ++u) {
;         const int sl2 = j & 1;
;         const int st = j * 2 + u;
;         const f32x4 a4 = La[sl2][u], b4 = Lb[sl2][u], w4 = Lw[sl2][u], kd = Lk[sl2][u], r4 = Lr[sl2][u];
;         const float vv = Lv[sl2][u];
;         f32x2 p = S01 * a4.xy;
;         p = S23 * a4.zw + p;
;         float sa = p.x + p.y;
;         sa += dppf(sa, 0); yprev += dppf(yprev, 0);
;         sa += dppf(sa, 1); yprev += dppf(yprev, 1);
;         sa += dppf(sa, 2); yprev += dppf(yprev, 2);
;         sa += dppf(sa, 3); yprev += dppf(yprev, 3);
;         if (st >= 1 && st <= 16) ykeep0 = (kq == st - 1) ? yprev : ykeep0;
;         if (st >= 17) ykeep1 = (kq == st - 17) ? yprev : ykeep1;
;         const f32x2 sa2 = (f32x2){sa, sa}, vv2 = (f32x2){vv, vv};
;         const f32x2 t01 = sa2 * b4.xy + vv2 * kd.xy;
;         const f32x2 t23 = sa2 * b4.zw + vv2 * kd.zw;
;         S01 = S01 * w4.xy + t01;
;         S23 = S23 * w4.zw + t23;
;         f32x2 q = S01 * r4.xy;
;         q = S23 * r4.zw + q;
;         yprev = q.x + q.y;
;       }
	v_pk_mul_f32 v[130:131], v[30:31], v[46:47]
	v_pk_mul_f32 v[54:55], v[54:55], v[86:87] op_sel_hi:[1,0]
	v_pk_fma_f32 v[130:131], v[32:33], v[48:49], v[130:131]
	v_pk_mul_f32 v[56:57], v[56:57], v[86:87] op_sel_hi:[1,0]
	v_add_f32_e32 v130, v130, v131
	v_pk_fma_f32 v[54:55], v[30:31], v[50:51], v[54:55]
	v_pk_fma_f32 v[56:57], v[32:33], v[52:53], v[56:57]
	v_add_f32_dpp v130, v130, v130 quad_perm:[1,0,3,2] row_mask:0xf bank_mask:0xf bound_ctrl:1
	v_add_f32_dpp v134, v134, v134 quad_perm:[1,0,3,2] row_mask:0xf bank_mask:0xf bound_ctrl:1
	v_pk_mul_f32 v[132:133], v[124:125], v[30:31]
	v_add_f32_dpp v130, v130, v130 quad_perm:[2,3,0,1] row_mask:0xf bank_mask:0xf bound_ctrl:1
	v_add_f32_dpp v134, v134, v134 quad_perm:[2,3,0,1] row_mask:0xf bank_mask:0xf bound_ctrl:1
	v_pk_fma_f32 v[132:133], v[126:127], v[32:33], v[132:133]
	v_add_f32_dpp v130, v130, v130 row_half_mirror row_mask:0xf bank_mask:0xf bound_ctrl:1
	v_add_f32_dpp v134, v134, v134 row_half_mirror row_mask:0xf bank_mask:0xf bound_ctrl:1
	v_add_f32_e32 v132, v132, v133
	v_add_f32_dpp v130, v130, v130 row_mirror row_mask:0xf bank_mask:0xf bound_ctrl:1
	v_add_f32_dpp v134, v134, v134 row_mirror row_mask:0xf bank_mask:0xf bound_ctrl:1
	v_cndmask_b32_e64 v45, v45, v134, s[24:25]
	v_pk_fma_f32 v[30:31], v[58:59], v[130:131], v[54:55] op_sel_hi:[1,0,1]
	v_pk_fma_f32 v[32:33], v[60:61], v[130:131], v[56:57] op_sel_hi:[1,0,1]
	ds_read_b128 v[88:91], v34 offset:47104
	ds_read_b128 v[108:111], v34 offset:48640
	ds_read2st64_b32 v[128:129], v35 offset0:183 offset1:189
	ds_read_b128 v[96:99], v34 offset:46592
	ds_read_b128 v[92:95], v34 offset:46336
	ds_read_b128 v[100:103], v34 offset:47360
	ds_read_b128 v[104:107], v34 offset:46080
	ds_read_b128 v[116:119], v34 offset:48128
	ds_read_b128 v[112:115], v34 offset:47872
	ds_read_b128 v[120:123], v34 offset:48896
	ds_read_b128 v[124:127], v34 offset:47616
	v_pk_mul_f32 v[130:131], v[30:31], v[66:67]
	v_pk_mul_f32 v[74:75], v[74:75], v[86:87] op_sel:[0,1] op_sel_hi:[1,1]
	v_pk_fma_f32 v[130:131], v[32:33], v[68:69], v[130:131]
	v_pk_mul_f32 v[76:77], v[76:77], v[86:87] op_sel:[0,1] op_sel_hi:[1,1]
	v_add_f32_e32 v130, v130, v131
	v_pk_fma_f32 v[74:75], v[30:31], v[70:71], v[74:75]
	v_pk_fma_f32 v[76:77], v[32:33], v[72:73], v[76:77]
	v_add_f32_dpp v130, v130, v130 quad_perm:[1,0,3,2] row_mask:0xf bank_mask:0xf bound_ctrl:1
	v_add_f32_dpp v132, v132, v132 quad_perm:[1,0,3,2] row_mask:0xf bank_mask:0xf bound_ctrl:1
	v_pk_mul_f32 v[134:135], v[62:63], v[30:31]
	v_add_f32_dpp v130, v130, v130 quad_perm:[2,3,0,1] row_mask:0xf bank_mask:0xf bound_ctrl:1
	v_add_f32_dpp v132, v132, v132 quad_perm:[2,3,0,1] row_mask:0xf bank_mask:0xf bound_ctrl:1
	v_pk_fma_f32 v[134:135], v[64:65], v[32:33], v[134:135]
	v_add_f32_dpp v130, v130, v130 row_half_mirror row_mask:0xf bank_mask:0xf bound_ctrl:1
	v_add_f32_dpp v132, v132, v132 row_half_mirror row_mask:0xf bank_mask:0xf bound_ctrl:1
	v_add_f32_e32 v134, v134, v135
	v_add_f32_dpp v130, v130, v130 row_mirror row_mask:0xf bank_mask:0xf bound_ctrl:1
	v_add_f32_dpp v132, v132, v132 row_mirror row_mask:0xf bank_mask:0xf bound_ctrl:1
	v_cndmask_b32_e64 v45, v45, v132, s[26:27]
	v_pk_fma_f32 v[30:31], v[78:79], v[130:131], v[74:75] op_sel_hi:[1,0,1]
	v_pk_fma_f32 v[32:33], v[80:81], v[130:131], v[76:77] op_sel_hi:[1,0,1]
	s_waitcnt lgkmcnt(0)
; __device__ __forceinline__ void phase_scan(const Params& P, char* smem) {
;     ...
;     for (int j = 0; j < 16; ++j) {
;       if (j + 1 < 16) {
;         SCAN_LOADB(j + 1, (j + 1) & 1)
;       }
;       __builtin_amdgcn_sched_barrier(0);
; #pragma unroll
;       for (int u = 0; u < 2; ++u) {
;         const int sl2 = j & 1;
;         const int st = j * 2 + u;
;         const f32x4 a4 = La[sl2][u], b4 = Lb[sl2][u], w4 = Lw[sl2][u], kd = Lk[sl2][u], r4 = Lr[sl2][u];
;         const float vv = Lv[sl2][u];
;         f32x2 p = S01 * a4.xy;
;         p = S23 * a4.zw + p;
;         float sa = p.x + p.y;
;         sa += dppf(sa, 0); yprev += dppf(yprev, 0);
;         sa += dppf(sa, 1); yprev += dppf(yprev, 1);
;         sa += dppf(sa, 2); yprev += dppf(yprev, 2);
;         sa += dppf(sa, 3); yprev += dppf(yprev, 3);
;         if (st >= 1 && st <= 16) ykeep0 = (kq == st - 1) ? yprev : ykeep0;
;         if (st >= 17) ykeep1 = (kq == st - 17) ? yprev : ykeep1;
;         const f32x2 sa2 = (f32x2){sa, sa}, vv2 = (f32x2){vv, vv};
;         const f32x2 t01 = sa2 * b4.xy + vv2 * kd.xy;
;         const f32x2 t23 = sa2 * b4.zw + vv2 * kd.zw;
;         S01 = S01 * w4.xy + t01;
;         S23 = S23 * w4.zw + t23;
;         f32x2 q = S01 * r4.xy;
;         q = S23 * r4.zw + q;
;         yprev = q.x + q.y;
;       }
;     }
;     yprev = red16(yprev);
;     ykeep1 = (kq == 15) ? yprev : ykeep1;
;     {
;       const int kidx0 = kidx_of(ci * 32 + kq), kidx1 = kidx_of(ci * 32 + 16 + kq);
;       YZ[(size_t)(b * TPB + kidx0) * 512 + h * 64 + rg * 16 + rowl] = f2bf(ykeep0);
;       YZ[(size_t)(b * TPB + kidx1) * 512 + h * 64 + rg * 16 + rowl] = f2bf(ykeep1);
;     }
	v_pk_mul_f32 v[130:131], v[30:31], v[88:89]
	v_pk_mul_f32 v[96:97], v[96:97], v[128:129] op_sel_hi:[1,0]
	v_pk_fma_f32 v[130:131], v[32:33], v[90:91], v[130:131]
	v_pk_mul_f32 v[98:99], v[98:99], v[128:129] op_sel_hi:[1,0]
	v_add_f32_e32 v130, v130, v131
	v_pk_fma_f32 v[96:97], v[30:31], v[92:93], v[96:97]
	v_pk_fma_f32 v[98:99], v[32:33], v[94:95], v[98:99]
	v_add_f32_dpp v130, v130, v130 quad_perm:[1,0,3,2] row_mask:0xf bank_mask:0xf bound_ctrl:1
	v_add_f32_dpp v134, v134, v134 quad_perm:[1,0,3,2] row_mask:0xf bank_mask:0xf bound_ctrl:1
	v_pk_mul_f32 v[132:133], v[82:83], v[30:31]
	v_add_f32_dpp v130, v130, v130 quad_perm:[2,3,0,1] row_mask:0xf bank_mask:0xf bound_ctrl:1
	v_add_f32_dpp v134, v134, v134 quad_perm:[2,3,0,1] row_mask:0xf bank_mask:0xf bound_ctrl:1
	v_pk_fma_f32 v[132:133], v[84:85], v[32:33], v[132:133]
	v_add_f32_dpp v130, v130, v130 row_half_mirror row_mask:0xf bank_mask:0xf bound_ctrl:1
	v_add_f32_dpp v134, v134, v134 row_half_mirror row_mask:0xf bank_mask:0xf bound_ctrl:1
	v_add_f32_e32 v132, v132, v133
	v_add_f32_dpp v130, v130, v130 row_mirror row_mask:0xf bank_mask:0xf bound_ctrl:1
	v_add_f32_dpp v134, v134, v134 row_mirror row_mask:0xf bank_mask:0xf bound_ctrl:1
	v_cndmask_b32_e64 v45, v45, v134, s[28:29]
	v_pk_fma_f32 v[30:31], v[100:101], v[130:131], v[96:97] op_sel_hi:[1,0,1]
	v_pk_fma_f32 v[32:33], v[102:103], v[130:131], v[98:99] op_sel_hi:[1,0,1]
	v_pk_mul_f32 v[130:131], v[30:31], v[108:109]
	v_pk_mul_f32 v[116:117], v[116:117], v[128:129] op_sel:[0,1] op_sel_hi:[1,1]
	v_pk_fma_f32 v[130:131], v[32:33], v[110:111], v[130:131]
	v_pk_mul_f32 v[118:119], v[118:119], v[128:129] op_sel:[0,1] op_sel_hi:[1,1]
	v_add_f32_e32 v130, v130, v131
	v_pk_fma_f32 v[116:117], v[30:31], v[112:113], v[116:117]
	v_pk_fma_f32 v[118:119], v[32:33], v[114:115], v[118:119]
	v_add_f32_dpp v130, v130, v130 quad_perm:[1,0,3,2] row_mask:0xf bank_mask:0xf bound_ctrl:1
	v_add_f32_dpp v132, v132, v132 quad_perm:[1,0,3,2] row_mask:0xf bank_mask:0xf bound_ctrl:1
	v_pk_mul_f32 v[134:135], v[104:105], v[30:31]
	v_add_f32_dpp v130, v130, v130 quad_perm:[2,3,0,1] row_mask:0xf bank_mask:0xf bound_ctrl:1
	v_add_f32_dpp v132, v132, v132 quad_perm:[2,3,0,1] row_mask:0xf bank_mask:0xf bound_ctrl:1
	v_pk_fma_f32 v[134:135], v[106:107], v[32:33], v[134:135]
	v_add_f32_dpp v130, v130, v130 row_half_mirror row_mask:0xf bank_mask:0xf bound_ctrl:1
	v_add_f32_dpp v132, v132, v132 row_half_mirror row_mask:0xf bank_mask:0xf bound_ctrl:1
	v_add_f32_e32 v134, v134, v135
	v_add_f32_dpp v130, v130, v130 row_mirror row_mask:0xf bank_mask:0xf bound_ctrl:1
	v_add_f32_dpp v132, v132, v132 row_mirror row_mask:0xf bank_mask:0xf bound_ctrl:1
	v_cndmask_b32_e64 v45, v45, v132, s[30:31]
	v_pk_fma_f32 v[30:31], v[120:121], v[130:131], v[116:117] op_sel_hi:[1,0,1]
	v_pk_fma_f32 v[32:33], v[122:123], v[130:131], v[118:119] op_sel_hi:[1,0,1]
	v_pk_mul_f32 v[132:133], v[124:125], v[30:31]
	v_add_f32_dpp v134, v134, v134 quad_perm:[1,0,3,2] row_mask:0xf bank_mask:0xf bound_ctrl:1
	v_pk_fma_f32 v[132:133], v[126:127], v[32:33], v[132:133]
	s_nop 0
	v_add_f32_e32 v132, v132, v133
	v_add_f32_dpp v134, v134, v134 quad_perm:[2,3,0,1] row_mask:0xf bank_mask:0xf bound_ctrl:1
	s_nop 0
	v_add_f32_dpp v132, v132, v132 quad_perm:[1,0,3,2] row_mask:0xf bank_mask:0xf bound_ctrl:1
	v_add_f32_dpp v134, v134, v134 row_half_mirror row_mask:0xf bank_mask:0xf bound_ctrl:1
	s_nop 0
	v_add_f32_dpp v132, v132, v132 quad_perm:[2,3,0,1] row_mask:0xf bank_mask:0xf bound_ctrl:1
	v_add_f32_dpp v134, v134, v134 row_mirror row_mask:0xf bank_mask:0xf bound_ctrl:1
	s_nop 0
	v_add_f32_dpp v132, v132, v132 row_half_mirror row_mask:0xf bank_mask:0xf bound_ctrl:1
	v_cndmask_b32_e64 v45, v45, v134, s[34:35]
	s_nop 0
	v_add_f32_dpp v132, v132, v132 row_mirror row_mask:0xf bank_mask:0xf bound_ctrl:1
	v_cndmask_b32_e64 v45, v45, v132, s[0:1]
	s_cmp_gt_u32 s33, 7
	s_cselect_b32 s38, s10, 0xff
	s_add_i32 s33, s33, 1
	v_subrev_u32_e32 v37, 32, v37
	v_add_u32_e32 v47, s38, v36
	v_subrev_u32_e32 v36, 32, v36
	v_add_u32_e32 v46, s57, v181
	v_cndmask_b32_e32 v48, v47, v46, vcc
	v_add_u32_e32 v46, 16, v46
	v_add_u32_e32 v47, -16, v47
	v_cndmask_b32_e32 v47, v47, v46, vcc
	v_bfe_u32 v46, v44, 16, 1
	v_add3_u32 v49, v44, v46, s11
	v_add_u32_e32 v50, s2, v48
	v_ashrrev_i32_e32 v51, 31, v50
	v_lshlrev_b64 v[50:51], 10, v[50:51]
	v_lshl_add_u64 v[50:51], v[12:13], 0, v[50:51]
	global_store_short_d16_hi v[50:51], v49, off
	v_bfe_u32 v46, v45, 16, 1
	v_add3_u32 v52, v45, v46, s11
	v_add_u32_e32 v54, s2, v47
	v_ashrrev_i32_e32 v55, 31, v54
	v_lshlrev_b64 v[54:55], 10, v[54:55]
	s_add_i32 s57, s57, 32
	v_lshl_add_u64 v[54:55], v[12:13], 0, v[54:55]
	s_cmpk_eq_i32 s57, 0x4100
	global_store_short_d16_hi v[54:55], v52, off
	s_barrier
	s_cbranch_scc1 .LBB0_1309
